# baseline (speedup 1.0000x reference)
; DI unsigned pk_bf16(float lo, float hi) { f32x2_t v = {lo, hi}; return __builtin_bit_cast(unsigned, __builtin_convertvector(v, bf16x2_t)); }
; DI float bflo(unsigned u) { return __uint_as_float(u << 16); }
; DI float bfhi(unsigned u) { return __uint_as_float(u & 0xffff0000u); }
; DI float h2lo(unsigned u) { return (float)__builtin_bit_cast(f16x2_t, u)[0]; }
; DI float h2hi(unsigned u) { return (float)__builtin_bit_cast(f16x2_t, u)[1]; }
; #define EPI_M _Pragma("unroll") for (int m = 0; m < 8; ++m)
; #define EPI_N _Pragma("unroll") for (int n = 0; n < 4; ++n)
; #define EPI_N2 _Pragma("unroll") for (int n2 = 0; n2 < 2; ++n2)
; DI void p5_phase(const Params& p, char* lds) {
;     ...
;       u32x2 gq[2][4], rq[2][4];
;       EPI_N { gq[0][n] = tg[(0 * 4 + n) * 512 + tid]; rq[0][n] = tr[(0 * 4 + n) * 512 + tid]; }
;       EPI_M {
;         if (m < 7) EPI_N { gq[(m + 1) & 1][n] = tg[((m + 1) * 4 + n) * 512 + tid]; rq[(m + 1) & 1][n] = tr[((m + 1) * 4 + n) * 512 + tid]; }
;         EPI_N2 {
;           u32x4 o;
; #pragma unroll
;           for (int q = 0; q < 2; ++q) {
;             const int n = 2 * n2 + q;
;             const u32x2 g = gq[m & 1][n], r = rq[m & 1][n];
;             const float v0 = h2lo(r[0]) + ACC(m, n)[0] * bflo(g[0]), v1 = h2hi(r[0]) + ACC(m, n)[1] * bfhi(g[0]);
;             const float v2 = h2lo(r[1]) + ACC(m, n)[2] * bflo(g[1]), v3 = h2hi(r[1]) + ACC(m, n)[3] * bfhi(g[1]);
;             o[2 * q] = pk_bf16(v0, v1); o[2 * q + 1] = pk_bf16(v2, v3);
;           }
;           *(u32x4*)(mg + (size_t)EPI_ROW(row0, m) * 1024 + EPI_COL(col0, 2 * n2)) = o;
;         }
;         __builtin_amdgcn_sched_barrier(0);
;       }
;     }
.LBB0_969:
	s_or_b64 exec, exec, s[8:9]
	s_waitcnt vmcnt(0)
	s_barrier
	s_getreg_b32 s2, hwreg(HW_REG_HW_ID, 0, 6)
	s_lshl_b32 s2, s2, 2
	s_and_b32 s2, s2, 0xfc
	s_add_i32 s2, s2, 0x20040
	v_mov_b32_e32 v64, s2
	ds_read_b32 v64, v64
	s_waitcnt lgkmcnt(0)
	v_readfirstlane_b32 s2, v64
	s_nop 1
	v_lshl_or_b32 v132, s2, 6, v214
	s_movk_i32 s2, 0x2000
	v_ashrrev_i32_e32 v133, 31, v132
	v_lshlrev_b64 v[130:131], 3, v[132:133]
	v_lshl_add_u64 v[134:135], s[10:11], 0, v[130:131]
	v_add_co_u32_e32 v136, vcc, s2, v134
	v_lshl_add_u64 v[130:131], s[12:13], 0, v[130:131]
	s_nop 0
	v_addc_co_u32_e32 v137, vcc, 0, v135, vcc
	global_load_dwordx2 v[164:165], v[134:135], off
	global_load_dwordx2 v[166:167], v[136:137], off offset:-4096
	global_load_dwordx2 v[168:169], v[130:131], off
	v_add_co_u32_e32 v138, vcc, s2, v130
	v_ashrrev_i32_e32 v64, 2, v132
	s_nop 0
	v_addc_co_u32_e32 v139, vcc, 0, v131, vcc
	global_load_dwordx2 v[170:171], v[138:139], off offset:-4096
	global_load_dwordx2 v[154:155], v[136:137], off
	global_load_dwordx2 v[156:157], v[138:139], off
	v_add_co_u32_e32 v134, vcc, s75, v134
	v_and_b32_e32 v64, 0xffffffc0, v64
	s_nop 0
	v_addc_co_u32_e32 v135, vcc, 0, v135, vcc
	v_add_co_u32_e32 v130, vcc, s75, v130
	global_load_dwordx2 v[150:151], v[134:135], off
	s_nop 0
	v_addc_co_u32_e32 v131, vcc, 0, v131, vcc
	global_load_dwordx2 v[152:153], v[130:131], off
	v_add_u32_e32 v134, 0x800, v132
	v_ashrrev_i32_e32 v135, 31, v134
	v_lshlrev_b64 v[136:137], 3, v[134:135]
	v_lshl_add_u64 v[134:135], s[10:11], 0, v[136:137]
	v_lshl_add_u64 v[136:137], s[12:13], 0, v[136:137]
	global_load_dwordx2 v[134:135], v[134:135], off
	v_and_or_b32 v130, v132, 15, s40
	global_load_dwordx2 v[140:141], v[136:137], off
	v_add_u32_e32 v136, 0xa00, v132
	v_ashrrev_i32_e32 v137, 31, v136
	v_lshlrev_b64 v[136:137], 3, v[136:137]
	v_lshl_add_u64 v[138:139], s[10:11], 0, v[136:137]
	v_lshl_add_u64 v[136:137], s[12:13], 0, v[136:137]
	global_load_dwordx2 v[138:139], v[138:139], off
	v_add_u32_e32 v130, v130, v64
	global_load_dwordx2 v[148:149], v[136:137], off
	v_add_u32_e32 v136, 0xc00, v132
	v_ashrrev_i32_e32 v137, 31, v136
	v_lshlrev_b64 v[142:143], 3, v[136:137]
	v_lshl_add_u64 v[136:137], s[10:11], 0, v[142:143]
	v_lshl_add_u64 v[142:143], s[12:13], 0, v[142:143]
	global_load_dwordx2 v[136:137], v[136:137], off
	v_ashrrev_i32_e32 v131, 31, v130
	global_load_dwordx2 v[146:147], v[142:143], off
	v_add_u32_e32 v142, 0xe00, v132
	v_ashrrev_i32_e32 v143, 31, v142
	v_lshlrev_b64 v[142:143], 3, v[142:143]
	v_lshl_add_u64 v[144:145], s[10:11], 0, v[142:143]
	v_lshl_add_u64 v[142:143], s[12:13], 0, v[142:143]
	global_load_dwordx2 v[158:159], v[144:145], off
	global_load_dwordx2 v[162:163], v[142:143], off
	v_readlane_b32 s2, v253, 62
	v_lshlrev_b64 v[142:143], 11, v[130:131]
	v_readlane_b32 s3, v253, 63
	v_lshrrev_b32_e32 v64, 1, v132
	v_and_b32_e32 v64, 0x78, v64
	v_lshl_add_u64 v[172:173], s[2:3], 0, v[142:143]
	v_or_b32_e32 v160, s38, v64
	v_ashrrev_i32_e32 v161, 31, v160
	s_waitcnt vmcnt(15)
	v_lshlrev_b32_e32 v144, 16, v164
	v_and_b32_e32 v145, 0xffff0000, v164
	s_waitcnt vmcnt(13)
	v_cvt_f32_f16_e32 v142, v168
	v_cvt_f32_f16_sdwa v143, v168 dst_sel:DWORD dst_unused:UNUSED_PAD src0_sel:WORD_1
	v_pk_fma_f32 v[126:127], v[126:127], v[144:145], v[142:143]
	v_cvt_f32_f16_e32 v142, v169
	v_cvt_f32_f16_sdwa v143, v169 dst_sel:DWORD dst_unused:UNUSED_PAD src0_sel:WORD_1
	v_lshlrev_b32_e32 v144, 16, v165
	v_and_b32_e32 v145, 0xffff0000, v165
	v_cvt_pk_bf16_f32 v126, v126, v127
	v_pk_fma_f32 v[128:129], v[128:129], v[144:145], v[142:143]
	v_lshlrev_b32_e32 v142, 16, v166
	v_cvt_pk_bf16_f32 v127, v128, v129
	s_waitcnt vmcnt(12)
	v_cvt_f32_f16_e32 v128, v170
	v_cvt_f32_f16_sdwa v129, v170 dst_sel:DWORD dst_unused:UNUSED_PAD src0_sel:WORD_1
	v_and_b32_e32 v143, 0xffff0000, v166
	v_pk_fma_f32 v[122:123], v[122:123], v[142:143], v[128:129]
	v_cvt_f32_f16_e32 v128, v171
	v_cvt_f32_f16_sdwa v129, v171 dst_sel:DWORD dst_unused:UNUSED_PAD src0_sel:WORD_1
	v_lshlrev_b32_e32 v142, 16, v167
	v_and_b32_e32 v143, 0xffff0000, v167
	v_pk_fma_f32 v[124:125], v[124:125], v[142:143], v[128:129]
	v_cvt_pk_bf16_f32 v128, v122, v123
	v_lshlrev_b64 v[122:123], 1, v[160:161]
	v_cvt_pk_bf16_f32 v129, v124, v125
	v_lshl_add_u64 v[124:125], v[172:173], 0, v[122:123]
	global_store_dwordx4 v[124:125], v[126:129], off sc0 sc1
	s_waitcnt vmcnt(11)
	s_nop 0
	v_cvt_f32_f16_e32 v126, v156
	v_cvt_f32_f16_sdwa v127, v156 dst_sel:DWORD dst_unused:UNUSED_PAD src0_sel:WORD_1
	v_lshlrev_b32_e32 v128, 16, v154
	v_and_b32_e32 v129, 0xffff0000, v154
	v_pk_fma_f32 v[118:119], v[118:119], v[128:129], v[126:127]
	v_cvt_f32_f16_e32 v126, v157
	v_cvt_f32_f16_sdwa v127, v157 dst_sel:DWORD dst_unused:UNUSED_PAD src0_sel:WORD_1
	v_lshlrev_b32_e32 v128, 16, v155
	v_and_b32_e32 v129, 0xffff0000, v155
	v_cvt_pk_bf16_f32 v118, v118, v119
	v_pk_fma_f32 v[120:121], v[120:121], v[128:129], v[126:127]
	s_waitcnt vmcnt(10)
	v_lshlrev_b32_e32 v126, 16, v150
	v_cvt_pk_bf16_f32 v119, v120, v121
	s_waitcnt vmcnt(9)
; DI unsigned pk_bf16(float lo, float hi) { f32x2_t v = {lo, hi}; return __builtin_bit_cast(unsigned, __builtin_convertvector(v, bf16x2_t)); }
; DI float bflo(unsigned u) { return __uint_as_float(u << 16); }
; DI float bfhi(unsigned u) { return __uint_as_float(u & 0xffff0000u); }
; DI float h2lo(unsigned u) { return (float)__builtin_bit_cast(f16x2_t, u)[0]; }
; DI float h2hi(unsigned u) { return (float)__builtin_bit_cast(f16x2_t, u)[1]; }
; #define EPI_M _Pragma("unroll") for (int m = 0; m < 8; ++m)
; #define EPI_N _Pragma("unroll") for (int n = 0; n < 4; ++n)
; #define EPI_N2 _Pragma("unroll") for (int n2 = 0; n2 < 2; ++n2)
; DI void p5_phase(const Params& p, char* lds) {
;     ...
;       u32x2 gq[2][4], rq[2][4];
;       EPI_N { gq[0][n] = tg[(0 * 4 + n) * 512 + tid]; rq[0][n] = tr[(0 * 4 + n) * 512 + tid]; }
;       EPI_M {
;         if (m < 7) EPI_N { gq[(m + 1) & 1][n] = tg[((m + 1) * 4 + n) * 512 + tid]; rq[(m + 1) & 1][n] = tr[((m + 1) * 4 + n) * 512 + tid]; }
;         EPI_N2 {
;           u32x4 o;
; #pragma unroll
;           for (int q = 0; q < 2; ++q) {
;             const int n = 2 * n2 + q;
;             const u32x2 g = gq[m & 1][n], r = rq[m & 1][n];
;             const float v0 = h2lo(r[0]) + ACC(m, n)[0] * bflo(g[0]), v1 = h2hi(r[0]) + ACC(m, n)[1] * bfhi(g[0]);
;             const float v2 = h2lo(r[1]) + ACC(m, n)[2] * bflo(g[1]), v3 = h2hi(r[1]) + ACC(m, n)[3] * bfhi(g[1]);
;             o[2 * q] = pk_bf16(v0, v1); o[2 * q + 1] = pk_bf16(v2, v3);
;           }
;           *(u32x4*)(mg + (size_t)EPI_ROW(row0, m) * 1024 + EPI_COL(col0, 2 * n2)) = o;
;         }
;         __builtin_amdgcn_sched_barrier(0);
;       }
;     }
	v_cvt_f32_f16_e32 v120, v152
	v_cvt_f32_f16_sdwa v121, v152 dst_sel:DWORD dst_unused:UNUSED_PAD src0_sel:WORD_1
	v_and_b32_e32 v127, 0xffff0000, v150
	v_pk_fma_f32 v[114:115], v[114:115], v[126:127], v[120:121]
	v_cvt_f32_f16_e32 v120, v153
	v_cvt_f32_f16_sdwa v121, v153 dst_sel:DWORD dst_unused:UNUSED_PAD src0_sel:WORD_1
	v_lshlrev_b32_e32 v126, 16, v151
	v_and_b32_e32 v127, 0xffff0000, v151
	v_pk_fma_f32 v[116:117], v[116:117], v[126:127], v[120:121]
	v_cvt_pk_bf16_f32 v120, v114, v115
	v_cvt_pk_bf16_f32 v121, v116, v117
	global_store_dwordx4 v[124:125], v[118:121], off offset:256 sc0 sc1
	v_add_u32_e32 v114, 0x1000, v132
	v_ashrrev_i32_e32 v115, 31, v114
	v_lshlrev_b64 v[114:115], 3, v[114:115]
	v_lshl_add_u64 v[116:117], s[10:11], 0, v[114:115]
	v_lshl_add_u64 v[114:115], s[12:13], 0, v[114:115]
	global_load_dwordx2 v[126:127], v[116:117], off
	global_load_dwordx2 v[150:151], v[114:115], off
	v_add_u32_e32 v114, 0x1200, v132
	v_ashrrev_i32_e32 v115, 31, v114
	v_lshlrev_b64 v[114:115], 3, v[114:115]
	v_lshl_add_u64 v[116:117], s[10:11], 0, v[114:115]
	v_lshl_add_u64 v[114:115], s[12:13], 0, v[114:115]
	global_load_dwordx2 v[124:125], v[116:117], off
	global_load_dwordx2 v[128:129], v[114:115], off
	v_add_u32_e32 v114, 0x1400, v132
	v_ashrrev_i32_e32 v115, 31, v114
	v_lshlrev_b64 v[114:115], 3, v[114:115]
	v_lshl_add_u64 v[116:117], s[10:11], 0, v[114:115]
	v_lshl_add_u64 v[114:115], s[12:13], 0, v[114:115]
	global_load_dwordx2 v[116:117], v[116:117], off
	s_waitcnt vmcnt(13)
	v_cvt_f32_f16_e32 v144, v140
	global_load_dwordx2 v[120:121], v[114:115], off
	v_add_u32_e32 v114, 0x1600, v132
	v_ashrrev_i32_e32 v115, 31, v114
	v_lshlrev_b64 v[118:119], 3, v[114:115]
	v_lshl_add_u64 v[114:115], s[10:11], 0, v[118:119]
	v_lshl_add_u64 v[118:119], s[12:13], 0, v[118:119]
	global_load_dwordx2 v[114:115], v[114:115], off
	v_cvt_f32_f16_sdwa v145, v140 dst_sel:DWORD dst_unused:UNUSED_PAD src0_sel:WORD_1
	global_load_dwordx2 v[118:119], v[118:119], off
	v_cvt_f32_f16_e32 v140, v141
	v_cvt_f32_f16_sdwa v141, v141 dst_sel:DWORD dst_unused:UNUSED_PAD src0_sel:WORD_1
	v_lshlrev_b32_e32 v152, 16, v134
	v_and_b32_e32 v153, 0xffff0000, v134
	v_lshlrev_b32_e32 v134, 16, v135
	v_and_b32_e32 v135, 0xffff0000, v135
	v_pk_fma_f32 v[110:111], v[110:111], v[152:153], v[144:145]
	v_pk_fma_f32 v[112:113], v[112:113], v[134:135], v[140:141]
	v_cvt_pk_bf16_f32 v110, v110, v111
	v_cvt_pk_bf16_f32 v111, v112, v113
	s_waitcnt vmcnt(14)
	v_cvt_f32_f16_e32 v112, v148
	v_cvt_f32_f16_sdwa v113, v148 dst_sel:DWORD dst_unused:UNUSED_PAD src0_sel:WORD_1
	v_lshlrev_b32_e32 v134, 16, v138
	v_and_b32_e32 v135, 0xffff0000, v138
	v_or_b32_e32 v142, 16, v130
	v_pk_fma_f32 v[106:107], v[106:107], v[134:135], v[112:113]
	v_cvt_f32_f16_e32 v112, v149
	v_cvt_f32_f16_sdwa v113, v149 dst_sel:DWORD dst_unused:UNUSED_PAD src0_sel:WORD_1
	v_lshlrev_b32_e32 v134, 16, v139
	v_and_b32_e32 v135, 0xffff0000, v139
	v_ashrrev_i32_e32 v143, 31, v142
	v_pk_fma_f32 v[108:109], v[108:109], v[134:135], v[112:113]
	v_lshlrev_b64 v[142:143], 11, v[142:143]
	v_cvt_pk_bf16_f32 v113, v108, v109
	s_waitcnt vmcnt(12)
	v_cvt_f32_f16_e32 v108, v146
	v_cvt_f32_f16_sdwa v109, v146 dst_sel:DWORD dst_unused:UNUSED_PAD src0_sel:WORD_1
	v_lshl_add_u64 v[142:143], s[2:3], 0, v[142:143]
	v_cvt_pk_bf16_f32 v112, v106, v107
	v_lshl_add_u64 v[106:107], v[142:143], 0, v[122:123]
	global_store_dwordx4 v[106:107], v[110:113], off sc0 sc1
	s_nop 1
	v_lshlrev_b32_e32 v110, 16, v136
	v_and_b32_e32 v111, 0xffff0000, v136
	v_pk_fma_f32 v[102:103], v[102:103], v[110:111], v[108:109]
	v_cvt_f32_f16_e32 v108, v147
	v_cvt_f32_f16_sdwa v109, v147 dst_sel:DWORD dst_unused:UNUSED_PAD src0_sel:WORD_1
	v_lshlrev_b32_e32 v110, 16, v137
	v_and_b32_e32 v111, 0xffff0000, v137
	v_cvt_pk_bf16_f32 v102, v102, v103
	v_pk_fma_f32 v[104:105], v[104:105], v[110:111], v[108:109]
	s_waitcnt vmcnt(12)
	v_lshlrev_b32_e32 v108, 16, v158
	v_cvt_pk_bf16_f32 v103, v104, v105
	s_waitcnt vmcnt(11)
	v_cvt_f32_f16_e32 v104, v162
	v_cvt_f32_f16_sdwa v105, v162 dst_sel:DWORD dst_unused:UNUSED_PAD src0_sel:WORD_1
	v_and_b32_e32 v109, 0xffff0000, v158
	v_pk_fma_f32 v[98:99], v[98:99], v[108:109], v[104:105]
	v_cvt_f32_f16_e32 v104, v163
	v_cvt_f32_f16_sdwa v105, v163 dst_sel:DWORD dst_unused:UNUSED_PAD src0_sel:WORD_1
	v_lshlrev_b32_e32 v108, 16, v159
	v_and_b32_e32 v109, 0xffff0000, v159
	v_pk_fma_f32 v[100:101], v[100:101], v[108:109], v[104:105]
	v_cvt_pk_bf16_f32 v104, v98, v99
	v_cvt_pk_bf16_f32 v105, v100, v101
	global_store_dwordx4 v[106:107], v[102:105], off offset:256 sc0 sc1
	v_add_u32_e32 v98, 0x1800, v132
	v_ashrrev_i32_e32 v99, 31, v98
	v_lshlrev_b64 v[98:99], 3, v[98:99]
	v_lshl_add_u64 v[100:101], s[10:11], 0, v[98:99]
	v_lshl_add_u64 v[98:99], s[12:13], 0, v[98:99]
	global_load_dwordx2 v[108:109], v[100:101], off
	global_load_dwordx2 v[112:113], v[98:99], off
	v_add_u32_e32 v98, 0x1a00, v132
	v_ashrrev_i32_e32 v99, 31, v98
	v_lshlrev_b64 v[98:99], 3, v[98:99]
	v_lshl_add_u64 v[100:101], s[10:11], 0, v[98:99]
	v_lshl_add_u64 v[98:99], s[12:13], 0, v[98:99]
	global_load_dwordx2 v[106:107], v[100:101], off
	global_load_dwordx2 v[110:111], v[98:99], off
	v_add_u32_e32 v98, 0x1c00, v132
	v_ashrrev_i32_e32 v99, 31, v98
	v_lshlrev_b64 v[98:99], 3, v[98:99]
	v_lshl_add_u64 v[100:101], s[10:11], 0, v[98:99]
	v_lshl_add_u64 v[98:99], s[12:13], 0, v[98:99]
	global_load_dwordx2 v[100:101], v[100:101], off
	s_waitcnt vmcnt(13)
; DI unsigned pk_bf16(float lo, float hi) { f32x2_t v = {lo, hi}; return __builtin_bit_cast(unsigned, __builtin_convertvector(v, bf16x2_t)); }
; DI float bflo(unsigned u) { return __uint_as_float(u << 16); }
; DI float bfhi(unsigned u) { return __uint_as_float(u & 0xffff0000u); }
; DI float h2lo(unsigned u) { return (float)__builtin_bit_cast(f16x2_t, u)[0]; }
; DI float h2hi(unsigned u) { return (float)__builtin_bit_cast(f16x2_t, u)[1]; }
; #define EPI_M _Pragma("unroll") for (int m = 0; m < 8; ++m)
; #define EPI_N _Pragma("unroll") for (int n = 0; n < 4; ++n)
; #define EPI_N2 _Pragma("unroll") for (int n2 = 0; n2 < 2; ++n2)
; DI void p5_phase(const Params& p, char* lds) {
;     ...
;       u32x2 gq[2][4], rq[2][4];
;       EPI_N { gq[0][n] = tg[(0 * 4 + n) * 512 + tid]; rq[0][n] = tr[(0 * 4 + n) * 512 + tid]; }
;       EPI_M {
;         if (m < 7) EPI_N { gq[(m + 1) & 1][n] = tg[((m + 1) * 4 + n) * 512 + tid]; rq[(m + 1) & 1][n] = tr[((m + 1) * 4 + n) * 512 + tid]; }
;         EPI_N2 {
;           u32x4 o;
; #pragma unroll
;           for (int q = 0; q < 2; ++q) {
;             const int n = 2 * n2 + q;
;             const u32x2 g = gq[m & 1][n], r = rq[m & 1][n];
;             const float v0 = h2lo(r[0]) + ACC(m, n)[0] * bflo(g[0]), v1 = h2hi(r[0]) + ACC(m, n)[1] * bfhi(g[0]);
;             const float v2 = h2lo(r[1]) + ACC(m, n)[2] * bflo(g[1]), v3 = h2hi(r[1]) + ACC(m, n)[3] * bfhi(g[1]);
;             o[2 * q] = pk_bf16(v0, v1); o[2 * q + 1] = pk_bf16(v2, v3);
;           }
;           *(u32x4*)(mg + (size_t)EPI_ROW(row0, m) * 1024 + EPI_COL(col0, 2 * n2)) = o;
;         }
;         __builtin_amdgcn_sched_barrier(0);
;       }
;     }
	v_cvt_f32_f16_e32 v136, v150
	global_load_dwordx2 v[104:105], v[98:99], off
	v_add_u32_e32 v98, 0x1e00, v132
	v_ashrrev_i32_e32 v99, 31, v98
	v_lshlrev_b64 v[102:103], 3, v[98:99]
	v_lshl_add_u64 v[98:99], s[10:11], 0, v[102:103]
	v_lshl_add_u64 v[102:103], s[12:13], 0, v[102:103]
	global_load_dwordx2 v[98:99], v[98:99], off
	v_cvt_f32_f16_sdwa v137, v150 dst_sel:DWORD dst_unused:UNUSED_PAD src0_sel:WORD_1
	global_load_dwordx2 v[102:103], v[102:103], off
	v_lshlrev_b32_e32 v138, 16, v126
	v_and_b32_e32 v139, 0xffff0000, v126
	v_pk_fma_f32 v[94:95], v[94:95], v[138:139], v[136:137]
	v_cvt_f32_f16_e32 v136, v151
	v_cvt_f32_f16_sdwa v137, v151 dst_sel:DWORD dst_unused:UNUSED_PAD src0_sel:WORD_1
	v_lshlrev_b32_e32 v126, 16, v127
	v_and_b32_e32 v127, 0xffff0000, v127
	v_cvt_pk_bf16_f32 v94, v94, v95
	v_pk_fma_f32 v[96:97], v[96:97], v[126:127], v[136:137]
	s_waitcnt vmcnt(15)
	v_lshlrev_b32_e32 v126, 16, v124
	v_cvt_pk_bf16_f32 v95, v96, v97
	s_waitcnt vmcnt(14)
	v_cvt_f32_f16_e32 v96, v128
	v_cvt_f32_f16_sdwa v97, v128 dst_sel:DWORD dst_unused:UNUSED_PAD src0_sel:WORD_1
	v_and_b32_e32 v127, 0xffff0000, v124
	v_or_b32_e32 v134, 32, v130
	v_lshlrev_b32_e32 v124, 16, v125
	v_pk_fma_f32 v[90:91], v[90:91], v[126:127], v[96:97]
	v_cvt_f32_f16_e32 v96, v129
	v_cvt_f32_f16_sdwa v97, v129 dst_sel:DWORD dst_unused:UNUSED_PAD src0_sel:WORD_1
	v_and_b32_e32 v125, 0xffff0000, v125
	v_ashrrev_i32_e32 v135, 31, v134
	v_lshlrev_b64 v[134:135], 11, v[134:135]
	v_pk_fma_f32 v[92:93], v[92:93], v[124:125], v[96:97]
	v_lshl_add_u64 v[134:135], s[2:3], 0, v[134:135]
	v_cvt_pk_bf16_f32 v97, v92, v93
	s_waitcnt vmcnt(12)
	v_cvt_f32_f16_e32 v92, v120
	v_cvt_f32_f16_sdwa v93, v120 dst_sel:DWORD dst_unused:UNUSED_PAD src0_sel:WORD_1
	v_cvt_pk_bf16_f32 v96, v90, v91
	v_lshl_add_u64 v[90:91], v[134:135], 0, v[122:123]
	global_store_dwordx4 v[90:91], v[94:97], off sc0 sc1
	s_nop 1
	v_lshlrev_b32_e32 v94, 16, v116
	v_and_b32_e32 v95, 0xffff0000, v116
	v_pk_fma_f32 v[86:87], v[86:87], v[94:95], v[92:93]
	v_cvt_f32_f16_e32 v92, v121
	v_cvt_f32_f16_sdwa v93, v121 dst_sel:DWORD dst_unused:UNUSED_PAD src0_sel:WORD_1
	v_lshlrev_b32_e32 v94, 16, v117
	v_and_b32_e32 v95, 0xffff0000, v117
	v_cvt_pk_bf16_f32 v86, v86, v87
	v_pk_fma_f32 v[88:89], v[88:89], v[94:95], v[92:93]
	s_waitcnt vmcnt(12)
	v_lshlrev_b32_e32 v92, 16, v114
	v_cvt_pk_bf16_f32 v87, v88, v89
	s_waitcnt vmcnt(11)
	v_cvt_f32_f16_e32 v88, v118
	v_cvt_f32_f16_sdwa v89, v118 dst_sel:DWORD dst_unused:UNUSED_PAD src0_sel:WORD_1
	v_and_b32_e32 v93, 0xffff0000, v114
	v_pk_fma_f32 v[82:83], v[82:83], v[92:93], v[88:89]
	v_cvt_f32_f16_e32 v88, v119
	v_cvt_f32_f16_sdwa v89, v119 dst_sel:DWORD dst_unused:UNUSED_PAD src0_sel:WORD_1
	v_lshlrev_b32_e32 v92, 16, v115
	v_and_b32_e32 v93, 0xffff0000, v115
	v_pk_fma_f32 v[84:85], v[84:85], v[92:93], v[88:89]
	v_cvt_pk_bf16_f32 v88, v82, v83
	v_cvt_pk_bf16_f32 v89, v84, v85
	global_store_dwordx4 v[90:91], v[86:89], off offset:256 sc0 sc1
	v_add_u32_e32 v82, 0x2000, v132
	v_ashrrev_i32_e32 v83, 31, v82
	v_lshlrev_b64 v[82:83], 3, v[82:83]
	v_lshl_add_u64 v[84:85], s[10:11], 0, v[82:83]
	v_lshl_add_u64 v[82:83], s[12:13], 0, v[82:83]
	global_load_dwordx2 v[92:93], v[84:85], off
	global_load_dwordx2 v[96:97], v[82:83], off
	v_add_u32_e32 v82, 0x2200, v132
	v_ashrrev_i32_e32 v83, 31, v82
	v_lshlrev_b64 v[82:83], 3, v[82:83]
	v_lshl_add_u64 v[84:85], s[10:11], 0, v[82:83]
	v_lshl_add_u64 v[82:83], s[12:13], 0, v[82:83]
	global_load_dwordx2 v[90:91], v[84:85], off
	global_load_dwordx2 v[94:95], v[82:83], off
	v_add_u32_e32 v82, 0x2400, v132
	v_ashrrev_i32_e32 v83, 31, v82
	v_lshlrev_b64 v[82:83], 3, v[82:83]
	v_lshl_add_u64 v[84:85], s[10:11], 0, v[82:83]
	v_lshl_add_u64 v[82:83], s[12:13], 0, v[82:83]
	global_load_dwordx2 v[84:85], v[84:85], off
	s_waitcnt vmcnt(13)
	v_cvt_f32_f16_e32 v116, v112
	global_load_dwordx2 v[88:89], v[82:83], off
	v_add_u32_e32 v82, 0x2600, v132
	v_ashrrev_i32_e32 v83, 31, v82
	v_lshlrev_b64 v[86:87], 3, v[82:83]
	v_lshl_add_u64 v[82:83], s[10:11], 0, v[86:87]
	v_lshl_add_u64 v[86:87], s[12:13], 0, v[86:87]
	global_load_dwordx2 v[82:83], v[82:83], off
	v_cvt_f32_f16_sdwa v117, v112 dst_sel:DWORD dst_unused:UNUSED_PAD src0_sel:WORD_1
	global_load_dwordx2 v[86:87], v[86:87], off
	v_cvt_f32_f16_e32 v112, v113
	v_cvt_f32_f16_sdwa v113, v113 dst_sel:DWORD dst_unused:UNUSED_PAD src0_sel:WORD_1
	v_lshlrev_b32_e32 v118, 16, v108
	v_and_b32_e32 v119, 0xffff0000, v108
	v_lshlrev_b32_e32 v108, 16, v109
	v_and_b32_e32 v109, 0xffff0000, v109
	v_pk_fma_f32 v[78:79], v[78:79], v[118:119], v[116:117]
	v_pk_fma_f32 v[80:81], v[80:81], v[108:109], v[112:113]
	v_cvt_pk_bf16_f32 v78, v78, v79
	v_cvt_pk_bf16_f32 v79, v80, v81
	s_waitcnt vmcnt(14)
	v_cvt_f32_f16_e32 v80, v110
	v_cvt_f32_f16_sdwa v81, v110 dst_sel:DWORD dst_unused:UNUSED_PAD src0_sel:WORD_1
	v_lshlrev_b32_e32 v108, 16, v106
	v_and_b32_e32 v109, 0xffff0000, v106
	v_or_b32_e32 v114, 48, v130
	v_pk_fma_f32 v[74:75], v[74:75], v[108:109], v[80:81]
	v_cvt_f32_f16_e32 v80, v111
	v_cvt_f32_f16_sdwa v81, v111 dst_sel:DWORD dst_unused:UNUSED_PAD src0_sel:WORD_1
	v_lshlrev_b32_e32 v106, 16, v107
	v_and_b32_e32 v107, 0xffff0000, v107
	v_ashrrev_i32_e32 v115, 31, v114
	v_pk_fma_f32 v[76:77], v[76:77], v[106:107], v[80:81]
	v_lshlrev_b64 v[114:115], 11, v[114:115]
	v_cvt_pk_bf16_f32 v81, v76, v77
	s_waitcnt vmcnt(12)
; DI unsigned pk_bf16(float lo, float hi) { f32x2_t v = {lo, hi}; return __builtin_bit_cast(unsigned, __builtin_convertvector(v, bf16x2_t)); }
; DI float bflo(unsigned u) { return __uint_as_float(u << 16); }
; DI float bfhi(unsigned u) { return __uint_as_float(u & 0xffff0000u); }
; DI float h2lo(unsigned u) { return (float)__builtin_bit_cast(f16x2_t, u)[0]; }
; DI float h2hi(unsigned u) { return (float)__builtin_bit_cast(f16x2_t, u)[1]; }
; #define EPI_M _Pragma("unroll") for (int m = 0; m < 8; ++m)
; #define EPI_N _Pragma("unroll") for (int n = 0; n < 4; ++n)
; #define EPI_N2 _Pragma("unroll") for (int n2 = 0; n2 < 2; ++n2)
; DI void p5_phase(const Params& p, char* lds) {
;     ...
;       u32x2 gq[2][4], rq[2][4];
;       EPI_N { gq[0][n] = tg[(0 * 4 + n) * 512 + tid]; rq[0][n] = tr[(0 * 4 + n) * 512 + tid]; }
;       EPI_M {
;         if (m < 7) EPI_N { gq[(m + 1) & 1][n] = tg[((m + 1) * 4 + n) * 512 + tid]; rq[(m + 1) & 1][n] = tr[((m + 1) * 4 + n) * 512 + tid]; }
;         EPI_N2 {
;           u32x4 o;
; #pragma unroll
;           for (int q = 0; q < 2; ++q) {
;             const int n = 2 * n2 + q;
;             const u32x2 g = gq[m & 1][n], r = rq[m & 1][n];
;             const float v0 = h2lo(r[0]) + ACC(m, n)[0] * bflo(g[0]), v1 = h2hi(r[0]) + ACC(m, n)[1] * bfhi(g[0]);
;             const float v2 = h2lo(r[1]) + ACC(m, n)[2] * bflo(g[1]), v3 = h2hi(r[1]) + ACC(m, n)[3] * bfhi(g[1]);
;             o[2 * q] = pk_bf16(v0, v1); o[2 * q + 1] = pk_bf16(v2, v3);
;           }
;           *(u32x4*)(mg + (size_t)EPI_ROW(row0, m) * 1024 + EPI_COL(col0, 2 * n2)) = o;
;         }
;         __builtin_amdgcn_sched_barrier(0);
;       }
;     }
	v_cvt_f32_f16_e32 v76, v104
	v_cvt_f32_f16_sdwa v77, v104 dst_sel:DWORD dst_unused:UNUSED_PAD src0_sel:WORD_1
	v_lshl_add_u64 v[114:115], s[2:3], 0, v[114:115]
	v_cvt_pk_bf16_f32 v80, v74, v75
	v_lshl_add_u64 v[74:75], v[114:115], 0, v[122:123]
	global_store_dwordx4 v[74:75], v[78:81], off sc0 sc1
	s_nop 1
	v_lshlrev_b32_e32 v78, 16, v100
	v_and_b32_e32 v79, 0xffff0000, v100
	v_pk_fma_f32 v[70:71], v[70:71], v[78:79], v[76:77]
	v_cvt_f32_f16_e32 v76, v105
	v_cvt_f32_f16_sdwa v77, v105 dst_sel:DWORD dst_unused:UNUSED_PAD src0_sel:WORD_1
	v_lshlrev_b32_e32 v78, 16, v101
	v_and_b32_e32 v79, 0xffff0000, v101
	v_cvt_pk_bf16_f32 v70, v70, v71
	v_pk_fma_f32 v[72:73], v[72:73], v[78:79], v[76:77]
	s_waitcnt vmcnt(12)
	v_lshlrev_b32_e32 v76, 16, v98
	v_cvt_pk_bf16_f32 v71, v72, v73
	s_waitcnt vmcnt(11)
	v_cvt_f32_f16_e32 v72, v102
	v_cvt_f32_f16_sdwa v73, v102 dst_sel:DWORD dst_unused:UNUSED_PAD src0_sel:WORD_1
	v_and_b32_e32 v77, 0xffff0000, v98
	v_pk_fma_f32 v[66:67], v[66:67], v[76:77], v[72:73]
	v_cvt_f32_f16_e32 v72, v103
	v_cvt_f32_f16_sdwa v73, v103 dst_sel:DWORD dst_unused:UNUSED_PAD src0_sel:WORD_1
	v_lshlrev_b32_e32 v76, 16, v99
	v_and_b32_e32 v77, 0xffff0000, v99
	v_pk_fma_f32 v[68:69], v[68:69], v[76:77], v[72:73]
	v_cvt_pk_bf16_f32 v72, v66, v67
	v_cvt_pk_bf16_f32 v73, v68, v69
	global_store_dwordx4 v[74:75], v[70:73], off offset:256 sc0 sc1
	v_add_u32_e32 v66, 0x2800, v132
	v_ashrrev_i32_e32 v67, 31, v66
	v_lshlrev_b64 v[66:67], 3, v[66:67]
	v_lshl_add_u64 v[68:69], s[10:11], 0, v[66:67]
	v_lshl_add_u64 v[66:67], s[12:13], 0, v[66:67]
	global_load_dwordx2 v[76:77], v[68:69], off
	global_load_dwordx2 v[80:81], v[66:67], off
	v_add_u32_e32 v66, 0x2a00, v132
	v_ashrrev_i32_e32 v67, 31, v66
	v_lshlrev_b64 v[66:67], 3, v[66:67]
	v_lshl_add_u64 v[68:69], s[10:11], 0, v[66:67]
	v_lshl_add_u64 v[66:67], s[12:13], 0, v[66:67]
	global_load_dwordx2 v[74:75], v[68:69], off
	global_load_dwordx2 v[78:79], v[66:67], off
	v_add_u32_e32 v66, 0x2c00, v132
	v_ashrrev_i32_e32 v67, 31, v66
	v_lshlrev_b64 v[66:67], 3, v[66:67]
	v_lshl_add_u64 v[68:69], s[10:11], 0, v[66:67]
	v_lshl_add_u64 v[66:67], s[12:13], 0, v[66:67]
	global_load_dwordx2 v[68:69], v[68:69], off
	s_waitcnt vmcnt(13)
	v_cvt_f32_f16_e32 v100, v96
	global_load_dwordx2 v[72:73], v[66:67], off
	v_add_u32_e32 v66, 0x2e00, v132
	v_ashrrev_i32_e32 v67, 31, v66
	v_lshlrev_b64 v[70:71], 3, v[66:67]
	v_lshl_add_u64 v[66:67], s[10:11], 0, v[70:71]
	v_lshl_add_u64 v[70:71], s[12:13], 0, v[70:71]
	global_load_dwordx2 v[66:67], v[66:67], off
	v_cvt_f32_f16_sdwa v101, v96 dst_sel:DWORD dst_unused:UNUSED_PAD src0_sel:WORD_1
	global_load_dwordx2 v[70:71], v[70:71], off
	v_cvt_f32_f16_e32 v96, v97
	v_cvt_f32_f16_sdwa v97, v97 dst_sel:DWORD dst_unused:UNUSED_PAD src0_sel:WORD_1
	v_lshlrev_b32_e32 v102, 16, v92
	v_and_b32_e32 v103, 0xffff0000, v92
	v_lshlrev_b32_e32 v92, 16, v93
	v_and_b32_e32 v93, 0xffff0000, v93
	v_pk_fma_f32 v[60:61], v[60:61], v[102:103], v[100:101]
	v_pk_fma_f32 v[62:63], v[62:63], v[92:93], v[96:97]
	v_cvt_pk_bf16_f32 v60, v60, v61
	v_cvt_pk_bf16_f32 v61, v62, v63
	s_waitcnt vmcnt(14)
	v_cvt_f32_f16_e32 v62, v94
	v_cvt_f32_f16_sdwa v63, v94 dst_sel:DWORD dst_unused:UNUSED_PAD src0_sel:WORD_1
	v_lshlrev_b32_e32 v92, 16, v90
	v_and_b32_e32 v93, 0xffff0000, v90
	v_add_u32_e32 v98, 0x80, v130
	v_pk_fma_f32 v[56:57], v[56:57], v[92:93], v[62:63]
	v_cvt_f32_f16_e32 v62, v95
	v_cvt_f32_f16_sdwa v63, v95 dst_sel:DWORD dst_unused:UNUSED_PAD src0_sel:WORD_1
	v_lshlrev_b32_e32 v90, 16, v91
	v_and_b32_e32 v91, 0xffff0000, v91
	v_ashrrev_i32_e32 v99, 31, v98
	v_pk_fma_f32 v[58:59], v[58:59], v[90:91], v[62:63]
	v_lshlrev_b64 v[98:99], 11, v[98:99]
	v_cvt_pk_bf16_f32 v63, v58, v59
	s_waitcnt vmcnt(12)
	v_cvt_f32_f16_e32 v58, v88
	v_cvt_f32_f16_sdwa v59, v88 dst_sel:DWORD dst_unused:UNUSED_PAD src0_sel:WORD_1
	v_lshl_add_u64 v[98:99], s[2:3], 0, v[98:99]
	v_cvt_pk_bf16_f32 v62, v56, v57
	v_lshl_add_u64 v[56:57], v[98:99], 0, v[122:123]
	global_store_dwordx4 v[56:57], v[60:63], off sc0 sc1
	s_nop 1
	v_lshlrev_b32_e32 v60, 16, v84
	v_and_b32_e32 v61, 0xffff0000, v84
	v_pk_fma_f32 v[52:53], v[52:53], v[60:61], v[58:59]
	v_cvt_f32_f16_e32 v58, v89
	v_cvt_f32_f16_sdwa v59, v89 dst_sel:DWORD dst_unused:UNUSED_PAD src0_sel:WORD_1
	v_lshlrev_b32_e32 v60, 16, v85
	v_and_b32_e32 v61, 0xffff0000, v85
	v_cvt_pk_bf16_f32 v52, v52, v53
	v_pk_fma_f32 v[54:55], v[54:55], v[60:61], v[58:59]
	s_waitcnt vmcnt(12)
	v_lshlrev_b32_e32 v58, 16, v82
	v_cvt_pk_bf16_f32 v53, v54, v55
	s_waitcnt vmcnt(11)
	v_cvt_f32_f16_e32 v54, v86
	v_cvt_f32_f16_sdwa v55, v86 dst_sel:DWORD dst_unused:UNUSED_PAD src0_sel:WORD_1
	v_and_b32_e32 v59, 0xffff0000, v82
	v_pk_fma_f32 v[48:49], v[48:49], v[58:59], v[54:55]
	v_cvt_f32_f16_e32 v54, v87
	v_cvt_f32_f16_sdwa v55, v87 dst_sel:DWORD dst_unused:UNUSED_PAD src0_sel:WORD_1
	v_lshlrev_b32_e32 v58, 16, v83
	v_and_b32_e32 v59, 0xffff0000, v83
	v_pk_fma_f32 v[50:51], v[50:51], v[58:59], v[54:55]
	v_cvt_pk_bf16_f32 v54, v48, v49
	v_cvt_pk_bf16_f32 v55, v50, v51
	global_store_dwordx4 v[56:57], v[52:55], off offset:256 sc0 sc1
	v_add_u32_e32 v48, 0x3000, v132
	v_ashrrev_i32_e32 v49, 31, v48
	v_lshlrev_b64 v[48:49], 3, v[48:49]
	v_lshl_add_u64 v[50:51], s[10:11], 0, v[48:49]
	v_lshl_add_u64 v[48:49], s[12:13], 0, v[48:49]
	global_load_dwordx2 v[58:59], v[50:51], off
	global_load_dwordx2 v[62:63], v[48:49], off
	v_add_u32_e32 v48, 0x3200, v132
	v_ashrrev_i32_e32 v49, 31, v48
	v_lshlrev_b64 v[48:49], 3, v[48:49]
	v_lshl_add_u64 v[50:51], s[10:11], 0, v[48:49]
	v_lshl_add_u64 v[48:49], s[12:13], 0, v[48:49]
	global_load_dwordx2 v[56:57], v[50:51], off
	global_load_dwordx2 v[60:61], v[48:49], off
	v_add_u32_e32 v48, 0x3400, v132
	v_ashrrev_i32_e32 v49, 31, v48
	v_lshlrev_b64 v[48:49], 3, v[48:49]
	v_lshl_add_u64 v[50:51], s[10:11], 0, v[48:49]
	v_lshl_add_u64 v[48:49], s[12:13], 0, v[48:49]
	global_load_dwordx2 v[50:51], v[50:51], off
	s_waitcnt vmcnt(13)
; DI unsigned pk_bf16(float lo, float hi) { f32x2_t v = {lo, hi}; return __builtin_bit_cast(unsigned, __builtin_convertvector(v, bf16x2_t)); }
; DI float bflo(unsigned u) { return __uint_as_float(u << 16); }
; DI float bfhi(unsigned u) { return __uint_as_float(u & 0xffff0000u); }
; DI float h2lo(unsigned u) { return (float)__builtin_bit_cast(f16x2_t, u)[0]; }
; DI float h2hi(unsigned u) { return (float)__builtin_bit_cast(f16x2_t, u)[1]; }
; #define EPI_M _Pragma("unroll") for (int m = 0; m < 8; ++m)
; #define EPI_N _Pragma("unroll") for (int n = 0; n < 4; ++n)
; #define EPI_N2 _Pragma("unroll") for (int n2 = 0; n2 < 2; ++n2)
; DI void p5_phase(const Params& p, char* lds) {
;     ...
;       u32x2 gq[2][4], rq[2][4];
;       EPI_N { gq[0][n] = tg[(0 * 4 + n) * 512 + tid]; rq[0][n] = tr[(0 * 4 + n) * 512 + tid]; }
;       EPI_M {
;         if (m < 7) EPI_N { gq[(m + 1) & 1][n] = tg[((m + 1) * 4 + n) * 512 + tid]; rq[(m + 1) & 1][n] = tr[((m + 1) * 4 + n) * 512 + tid]; }
;         EPI_N2 {
;           u32x4 o;
; #pragma unroll
;           for (int q = 0; q < 2; ++q) {
;             const int n = 2 * n2 + q;
;             const u32x2 g = gq[m & 1][n], r = rq[m & 1][n];
;             const float v0 = h2lo(r[0]) + ACC(m, n)[0] * bflo(g[0]), v1 = h2hi(r[0]) + ACC(m, n)[1] * bfhi(g[0]);
;             const float v2 = h2lo(r[1]) + ACC(m, n)[2] * bflo(g[1]), v3 = h2hi(r[1]) + ACC(m, n)[3] * bfhi(g[1]);
;             o[2 * q] = pk_bf16(v0, v1); o[2 * q + 1] = pk_bf16(v2, v3);
;           }
;           *(u32x4*)(mg + (size_t)EPI_ROW(row0, m) * 1024 + EPI_COL(col0, 2 * n2)) = o;
;         }
;         __builtin_amdgcn_sched_barrier(0);
;       }
;     }
	v_cvt_f32_f16_e32 v84, v80
	global_load_dwordx2 v[54:55], v[48:49], off
	v_add_u32_e32 v48, 0x3600, v132
	v_ashrrev_i32_e32 v49, 31, v48
	v_lshlrev_b64 v[52:53], 3, v[48:49]
	v_lshl_add_u64 v[48:49], s[10:11], 0, v[52:53]
	v_lshl_add_u64 v[52:53], s[12:13], 0, v[52:53]
	global_load_dwordx2 v[48:49], v[48:49], off
	v_cvt_f32_f16_sdwa v85, v80 dst_sel:DWORD dst_unused:UNUSED_PAD src0_sel:WORD_1
	global_load_dwordx2 v[52:53], v[52:53], off
	v_cvt_f32_f16_e32 v80, v81
	v_cvt_f32_f16_sdwa v81, v81 dst_sel:DWORD dst_unused:UNUSED_PAD src0_sel:WORD_1
	v_lshlrev_b32_e32 v86, 16, v76
	v_and_b32_e32 v87, 0xffff0000, v76
	v_lshlrev_b32_e32 v76, 16, v77
	v_and_b32_e32 v77, 0xffff0000, v77
	v_pk_fma_f32 v[44:45], v[44:45], v[86:87], v[84:85]
	v_pk_fma_f32 v[46:47], v[46:47], v[76:77], v[80:81]
	v_cvt_pk_bf16_f32 v44, v44, v45
	v_cvt_pk_bf16_f32 v45, v46, v47
	s_waitcnt vmcnt(14)
	v_cvt_f32_f16_e32 v46, v78
	v_cvt_f32_f16_sdwa v47, v78 dst_sel:DWORD dst_unused:UNUSED_PAD src0_sel:WORD_1
	v_lshlrev_b32_e32 v76, 16, v74
	v_and_b32_e32 v77, 0xffff0000, v74
	v_add_u32_e32 v82, 0x90, v130
	v_pk_fma_f32 v[40:41], v[40:41], v[76:77], v[46:47]
	v_cvt_f32_f16_e32 v46, v79
	v_cvt_f32_f16_sdwa v47, v79 dst_sel:DWORD dst_unused:UNUSED_PAD src0_sel:WORD_1
	v_lshlrev_b32_e32 v74, 16, v75
	v_and_b32_e32 v75, 0xffff0000, v75
	v_ashrrev_i32_e32 v83, 31, v82
	v_pk_fma_f32 v[42:43], v[42:43], v[74:75], v[46:47]
	v_lshlrev_b64 v[82:83], 11, v[82:83]
	v_cvt_pk_bf16_f32 v47, v42, v43
	s_waitcnt vmcnt(12)
	v_cvt_f32_f16_e32 v42, v72
	v_cvt_f32_f16_sdwa v43, v72 dst_sel:DWORD dst_unused:UNUSED_PAD src0_sel:WORD_1
	v_lshl_add_u64 v[82:83], s[2:3], 0, v[82:83]
	v_cvt_pk_bf16_f32 v46, v40, v41
	v_lshl_add_u64 v[40:41], v[82:83], 0, v[122:123]
	global_store_dwordx4 v[40:41], v[44:47], off sc0 sc1
	s_nop 1
	v_lshlrev_b32_e32 v44, 16, v68
	v_and_b32_e32 v45, 0xffff0000, v68
	v_pk_fma_f32 v[36:37], v[36:37], v[44:45], v[42:43]
	v_cvt_f32_f16_e32 v42, v73
	v_cvt_f32_f16_sdwa v43, v73 dst_sel:DWORD dst_unused:UNUSED_PAD src0_sel:WORD_1
	v_lshlrev_b32_e32 v44, 16, v69
	v_and_b32_e32 v45, 0xffff0000, v69
	v_cvt_pk_bf16_f32 v36, v36, v37
	v_pk_fma_f32 v[38:39], v[38:39], v[44:45], v[42:43]
	s_waitcnt vmcnt(12)
	v_lshlrev_b32_e32 v42, 16, v66
	v_cvt_pk_bf16_f32 v37, v38, v39
	s_waitcnt vmcnt(11)
	v_cvt_f32_f16_e32 v38, v70
	v_cvt_f32_f16_sdwa v39, v70 dst_sel:DWORD dst_unused:UNUSED_PAD src0_sel:WORD_1
	v_and_b32_e32 v43, 0xffff0000, v66
	v_pk_fma_f32 v[32:33], v[32:33], v[42:43], v[38:39]
	v_cvt_f32_f16_e32 v38, v71
	v_cvt_f32_f16_sdwa v39, v71 dst_sel:DWORD dst_unused:UNUSED_PAD src0_sel:WORD_1
	v_lshlrev_b32_e32 v42, 16, v67
	v_and_b32_e32 v43, 0xffff0000, v67
	v_pk_fma_f32 v[34:35], v[34:35], v[42:43], v[38:39]
	v_cvt_pk_bf16_f32 v38, v32, v33
	v_cvt_pk_bf16_f32 v39, v34, v35
	global_store_dwordx4 v[40:41], v[36:39], off offset:256 sc0 sc1
	v_add_u32_e32 v32, 0x3800, v132
	v_ashrrev_i32_e32 v33, 31, v32
	v_lshlrev_b64 v[32:33], 3, v[32:33]
	v_lshl_add_u64 v[34:35], s[10:11], 0, v[32:33]
	v_lshl_add_u64 v[32:33], s[12:13], 0, v[32:33]
	global_load_dwordx2 v[38:39], v[34:35], off
	global_load_dwordx2 v[40:41], v[32:33], off
	v_add_u32_e32 v32, 0x3a00, v132
	v_ashrrev_i32_e32 v33, 31, v32
	v_lshlrev_b64 v[32:33], 3, v[32:33]
	v_lshl_add_u64 v[34:35], s[10:11], 0, v[32:33]
	v_lshl_add_u64 v[32:33], s[12:13], 0, v[32:33]
	global_load_dwordx2 v[42:43], v[34:35], off
	global_load_dwordx2 v[44:45], v[32:33], off
	v_add_u32_e32 v32, 0x3c00, v132
	v_ashrrev_i32_e32 v33, 31, v32
	v_lshlrev_b64 v[32:33], 3, v[32:33]
	v_lshl_add_u64 v[34:35], s[10:11], 0, v[32:33]
	v_lshl_add_u64 v[32:33], s[12:13], 0, v[32:33]
	global_load_dwordx2 v[34:35], v[34:35], off
	s_waitcnt vmcnt(13)
	v_cvt_f32_f16_e32 v68, v62
	global_load_dwordx2 v[46:47], v[32:33], off
	v_add_u32_e32 v32, 0x3e00, v132
	v_ashrrev_i32_e32 v33, 31, v32
	v_lshlrev_b64 v[36:37], 3, v[32:33]
	v_lshl_add_u64 v[32:33], s[10:11], 0, v[36:37]
	v_lshl_add_u64 v[36:37], s[12:13], 0, v[36:37]
	global_load_dwordx2 v[32:33], v[32:33], off
	v_cvt_f32_f16_sdwa v69, v62 dst_sel:DWORD dst_unused:UNUSED_PAD src0_sel:WORD_1
	global_load_dwordx2 v[36:37], v[36:37], off
	v_cvt_f32_f16_e32 v62, v63
	v_cvt_f32_f16_sdwa v63, v63 dst_sel:DWORD dst_unused:UNUSED_PAD src0_sel:WORD_1
	v_lshlrev_b32_e32 v70, 16, v58
	v_and_b32_e32 v71, 0xffff0000, v58
	v_lshlrev_b32_e32 v58, 16, v59
	v_and_b32_e32 v59, 0xffff0000, v59
	v_pk_fma_f32 v[28:29], v[28:29], v[70:71], v[68:69]
	v_pk_fma_f32 v[30:31], v[30:31], v[58:59], v[62:63]
	v_cvt_pk_bf16_f32 v28, v28, v29
	v_cvt_pk_bf16_f32 v29, v30, v31
	s_waitcnt vmcnt(14)
; DI unsigned pk_bf16(float lo, float hi) { f32x2_t v = {lo, hi}; return __builtin_bit_cast(unsigned, __builtin_convertvector(v, bf16x2_t)); }
; DI float bflo(unsigned u) { return __uint_as_float(u << 16); }
; DI float bfhi(unsigned u) { return __uint_as_float(u & 0xffff0000u); }
; DI float h2lo(unsigned u) { return (float)__builtin_bit_cast(f16x2_t, u)[0]; }
; DI float h2hi(unsigned u) { return (float)__builtin_bit_cast(f16x2_t, u)[1]; }
; #define EPI_M _Pragma("unroll") for (int m = 0; m < 8; ++m)
; #define EPI_N _Pragma("unroll") for (int n = 0; n < 4; ++n)
; #define EPI_N2 _Pragma("unroll") for (int n2 = 0; n2 < 2; ++n2)
; DI void p5_phase(const Params& p, char* lds) {
;     ...
;       u32x2 gq[2][4], rq[2][4];
;       EPI_N { gq[0][n] = tg[(0 * 4 + n) * 512 + tid]; rq[0][n] = tr[(0 * 4 + n) * 512 + tid]; }
;       EPI_M {
;         if (m < 7) EPI_N { gq[(m + 1) & 1][n] = tg[((m + 1) * 4 + n) * 512 + tid]; rq[(m + 1) & 1][n] = tr[((m + 1) * 4 + n) * 512 + tid]; }
;         EPI_N2 {
;           u32x4 o;
; #pragma unroll
;           for (int q = 0; q < 2; ++q) {
;             const int n = 2 * n2 + q;
;             const u32x2 g = gq[m & 1][n], r = rq[m & 1][n];
;             const float v0 = h2lo(r[0]) + ACC(m, n)[0] * bflo(g[0]), v1 = h2hi(r[0]) + ACC(m, n)[1] * bfhi(g[0]);
;             const float v2 = h2lo(r[1]) + ACC(m, n)[2] * bflo(g[1]), v3 = h2hi(r[1]) + ACC(m, n)[3] * bfhi(g[1]);
;             o[2 * q] = pk_bf16(v0, v1); o[2 * q + 1] = pk_bf16(v2, v3);
;           }
;           *(u32x4*)(mg + (size_t)EPI_ROW(row0, m) * 1024 + EPI_COL(col0, 2 * n2)) = o;
;         }
;         __builtin_amdgcn_sched_barrier(0);
;       }
;     }
	v_cvt_f32_f16_e32 v30, v60
	v_cvt_f32_f16_sdwa v31, v60 dst_sel:DWORD dst_unused:UNUSED_PAD src0_sel:WORD_1
	v_lshlrev_b32_e32 v58, 16, v56
	v_and_b32_e32 v59, 0xffff0000, v56
	v_add_u32_e32 v66, 0xa0, v130
	v_pk_fma_f32 v[24:25], v[24:25], v[58:59], v[30:31]
	v_cvt_f32_f16_e32 v30, v61
	v_cvt_f32_f16_sdwa v31, v61 dst_sel:DWORD dst_unused:UNUSED_PAD src0_sel:WORD_1
	v_lshlrev_b32_e32 v56, 16, v57
	v_and_b32_e32 v57, 0xffff0000, v57
	v_ashrrev_i32_e32 v67, 31, v66
	v_pk_fma_f32 v[26:27], v[26:27], v[56:57], v[30:31]
	v_lshlrev_b64 v[66:67], 11, v[66:67]
	v_cvt_pk_bf16_f32 v31, v26, v27
	s_waitcnt vmcnt(12)
	v_cvt_f32_f16_e32 v26, v54
	v_cvt_f32_f16_sdwa v27, v54 dst_sel:DWORD dst_unused:UNUSED_PAD src0_sel:WORD_1
	v_lshl_add_u64 v[66:67], s[2:3], 0, v[66:67]
	v_cvt_pk_bf16_f32 v30, v24, v25
	v_lshl_add_u64 v[24:25], v[66:67], 0, v[122:123]
	global_store_dwordx4 v[24:25], v[28:31], off sc0 sc1
	s_nop 1
	v_lshlrev_b32_e32 v28, 16, v50
	v_and_b32_e32 v29, 0xffff0000, v50
	v_pk_fma_f32 v[20:21], v[20:21], v[28:29], v[26:27]
	v_cvt_f32_f16_e32 v26, v55
	v_cvt_f32_f16_sdwa v27, v55 dst_sel:DWORD dst_unused:UNUSED_PAD src0_sel:WORD_1
	v_lshlrev_b32_e32 v28, 16, v51
	v_and_b32_e32 v29, 0xffff0000, v51
	v_cvt_pk_bf16_f32 v20, v20, v21
	v_pk_fma_f32 v[22:23], v[22:23], v[28:29], v[26:27]
	s_waitcnt vmcnt(12)
	v_lshlrev_b32_e32 v26, 16, v48
	v_cvt_pk_bf16_f32 v21, v22, v23
	s_waitcnt vmcnt(11)
	v_cvt_f32_f16_e32 v22, v52
	v_cvt_f32_f16_sdwa v23, v52 dst_sel:DWORD dst_unused:UNUSED_PAD src0_sel:WORD_1
	v_and_b32_e32 v27, 0xffff0000, v48
	v_pk_fma_f32 v[16:17], v[16:17], v[26:27], v[22:23]
	v_cvt_f32_f16_e32 v22, v53
	v_cvt_f32_f16_sdwa v23, v53 dst_sel:DWORD dst_unused:UNUSED_PAD src0_sel:WORD_1
	v_lshlrev_b32_e32 v26, 16, v49
	v_and_b32_e32 v27, 0xffff0000, v49
	v_pk_fma_f32 v[18:19], v[18:19], v[26:27], v[22:23]
	v_cvt_pk_bf16_f32 v22, v16, v17
	v_cvt_pk_bf16_f32 v23, v18, v19
	global_store_dwordx4 v[24:25], v[20:23], off offset:256 sc0 sc1
	s_waitcnt vmcnt(8)
	v_cvt_f32_f16_e32 v18, v40
	v_cvt_f32_f16_sdwa v19, v40 dst_sel:DWORD dst_unused:UNUSED_PAD src0_sel:WORD_1
	v_lshlrev_b32_e32 v20, 16, v38
	v_and_b32_e32 v21, 0xffff0000, v38
	v_add_u32_e32 v16, 0xb0, v130
	v_pk_fma_f32 v[12:13], v[12:13], v[20:21], v[18:19]
	v_cvt_f32_f16_e32 v18, v41
	v_cvt_f32_f16_sdwa v19, v41 dst_sel:DWORD dst_unused:UNUSED_PAD src0_sel:WORD_1
	v_lshlrev_b32_e32 v20, 16, v39
	v_and_b32_e32 v21, 0xffff0000, v39
	v_cvt_pk_bf16_f32 v12, v12, v13
	v_pk_fma_f32 v[14:15], v[14:15], v[20:21], v[18:19]
	s_waitcnt vmcnt(7)
	v_lshlrev_b32_e32 v18, 16, v42
	v_cvt_pk_bf16_f32 v13, v14, v15
	s_waitcnt vmcnt(6)
	v_cvt_f32_f16_e32 v14, v44
	v_cvt_f32_f16_sdwa v15, v44 dst_sel:DWORD dst_unused:UNUSED_PAD src0_sel:WORD_1
	v_and_b32_e32 v19, 0xffff0000, v42
	v_ashrrev_i32_e32 v17, 31, v16
	v_lshlrev_b64 v[16:17], 11, v[16:17]
	v_pk_fma_f32 v[8:9], v[8:9], v[18:19], v[14:15]
	v_cvt_f32_f16_e32 v14, v45
	v_cvt_f32_f16_sdwa v15, v45 dst_sel:DWORD dst_unused:UNUSED_PAD src0_sel:WORD_1
	v_lshlrev_b32_e32 v18, 16, v43
	v_and_b32_e32 v19, 0xffff0000, v43
	v_lshl_add_u64 v[16:17], s[2:3], 0, v[16:17]
	v_pk_fma_f32 v[10:11], v[10:11], v[18:19], v[14:15]
	v_cvt_pk_bf16_f32 v14, v8, v9
	v_cvt_pk_bf16_f32 v15, v10, v11
	s_waitcnt vmcnt(4)
	v_cvt_f32_f16_e32 v10, v46
	v_cvt_f32_f16_sdwa v11, v46 dst_sel:DWORD dst_unused:UNUSED_PAD src0_sel:WORD_1
	v_lshl_add_u64 v[8:9], v[16:17], 0, v[122:123]
	global_store_dwordx4 v[8:9], v[12:15], off sc0 sc1
	s_nop 1
	v_lshlrev_b32_e32 v12, 16, v34
	v_and_b32_e32 v13, 0xffff0000, v34
	v_pk_fma_f32 v[4:5], v[4:5], v[12:13], v[10:11]
	v_cvt_f32_f16_e32 v10, v47
	v_cvt_f32_f16_sdwa v11, v47 dst_sel:DWORD dst_unused:UNUSED_PAD src0_sel:WORD_1
	v_lshlrev_b32_e32 v12, 16, v35
	v_and_b32_e32 v13, 0xffff0000, v35
	v_cvt_pk_bf16_f32 v4, v4, v5
	v_pk_fma_f32 v[6:7], v[6:7], v[12:13], v[10:11]
	s_waitcnt vmcnt(4)
	v_lshlrev_b32_e32 v10, 16, v32
	v_cvt_pk_bf16_f32 v5, v6, v7
	s_waitcnt vmcnt(3)
	v_cvt_f32_f16_e32 v6, v36
	v_cvt_f32_f16_sdwa v7, v36 dst_sel:DWORD dst_unused:UNUSED_PAD src0_sel:WORD_1
	v_and_b32_e32 v11, 0xffff0000, v32
	v_pk_fma_f32 v[0:1], v[0:1], v[10:11], v[6:7]
	v_cvt_f32_f16_e32 v6, v37
	v_cvt_f32_f16_sdwa v7, v37 dst_sel:DWORD dst_unused:UNUSED_PAD src0_sel:WORD_1
	v_lshlrev_b32_e32 v10, 16, v33
	v_and_b32_e32 v11, 0xffff0000, v33
	v_pk_fma_f32 v[2:3], v[2:3], v[10:11], v[6:7]
	v_cvt_pk_bf16_f32 v6, v0, v1
	v_cvt_pk_bf16_f32 v7, v2, v3
	global_store_dwordx4 v[8:9], v[4:7], off offset:256 sc0 sc1
	v_readlane_b32 s2, v255, 7
	s_add_i32 s36, s36, s2
	s_cmpk_lt_i32 s36, 0x100
	v_readlane_b32 s3, v255, 8
	s_cbranch_scc0 .LBB0_994

; DI unsigned pk_f16(float lo, float hi) { f32x2_t v = {lo, hi}; return __builtin_bit_cast(unsigned, __builtin_convertvector(v, f16x2_t)); }
; DI float bflo(unsigned u) { return __uint_as_float(u << 16); }
; DI float bfhi(unsigned u) { return __uint_as_float(u & 0xffff0000u); }
; #define EPI_M _Pragma("unroll") for (int m = 0; m < 8; ++m)
; #define EPI_N2 _Pragma("unroll") for (int n2 = 0; n2 < 2; ++n2)
; DI void p6_phase(const Params& p, const float* xin, u16* dst, char* lds) {
;     ...
;     {
;       const u16* xinb = (const u16*)(ws + OFF_XB);
;       u32x4 xq[2][2];
;       EPI_N2 xq[0][n2] = *(const u32x4*)(xinb + (size_t)EPI_ROW(row0, 0) * D + EPI_COL(col0, 2 * n2));
;       EPI_M {
;         if (m < 7) EPI_N2 xq[(m + 1) & 1][n2] = *(const u32x4*)(xinb + (size_t)EPI_ROW(row0, m + 1) * D + EPI_COL(col0, 2 * n2));
;         EPI_N2 {
;           const u32x4 r = xq[m & 1][n2];
;           const f32x4 xa = {bflo(r[0]), bfhi(r[0]), bflo(r[1]), bfhi(r[1])}, xc = {bflo(r[2]), bfhi(r[2]), bflo(r[3]), bfhi(r[3])};
;           const f32x4 ya = xa * DN_ALPHA + ACC(m, 2 * n2), yc = xc * DN_ALPHA + ACC(m, 2 * n2 + 1);
;           u32x4 yo; yo[0] = pk_f16(ya[0], ya[1]); yo[1] = pk_f16(ya[2], ya[3]); yo[2] = pk_f16(yc[0], yc[1]); yo[3] = pk_f16(yc[2], yc[3]);
;           *(u32x4*)(dst + (size_t)EPI_ROW(row0, m) * D + EPI_COL(col0, 2 * n2)) = yo;
;         }
;         __builtin_amdgcn_sched_barrier(0);
;       }
;     }
.LBB0_1049:
	s_or_b64 exec, exec, s[28:29]
	s_waitcnt vmcnt(0)
	s_barrier
	s_getreg_b32 s3, hwreg(HW_REG_HW_ID, 0, 6)
	s_lshl_b32 s3, s3, 2
	s_and_b32 s3, s3, 0xfc
	s_add_i32 s3, s3, 0x20040
	v_mov_b32_e32 v64, s3
	ds_read_b32 v64, v64
	v_readlane_b32 s28, v254, 22
	v_readlane_b32 s29, v254, 23
	s_waitcnt lgkmcnt(0)
	v_readfirstlane_b32 s3, v64
	s_nop 1
	v_lshl_or_b32 v64, s3, 6, v214
	s_nop 0
	v_ashrrev_i32_e32 v122, 2, v64
	v_and_b32_e32 v137, 0xffffffc0, v122
	v_and_b32_e32 v136, 15, v64
	v_add_u32_e32 v122, s8, v137
	v_lshrrev_b32_e32 v64, 1, v64
	v_or_b32_e32 v122, v122, v136
	v_and_b32_e32 v64, 0x78, v64
	v_ashrrev_i32_e32 v123, 31, v122
	v_or_b32_e32 v124, s22, v64
	v_lshlrev_b64 v[122:123], 11, v[122:123]
	v_ashrrev_i32_e32 v125, 31, v124
	v_lshl_add_u64 v[122:123], s[28:29], 0, v[122:123]
	v_lshlrev_b64 v[134:135], 1, v[124:125]
	v_or_b32_e32 v64, s8, v136
	v_lshl_add_u64 v[122:123], v[122:123], 0, v[134:135]
	v_add_u32_e32 v136, v64, v137
	global_load_dwordx4 v[138:141], v[122:123], off
	global_load_dwordx4 v[142:145], v[122:123], off offset:256
	v_or_b32_e32 v122, 16, v136
	v_ashrrev_i32_e32 v123, 31, v122
	v_lshlrev_b64 v[150:151], 11, v[122:123]
	v_lshl_add_u64 v[122:123], s[28:29], 0, v[150:151]
	v_lshl_add_u64 v[122:123], v[122:123], 0, v[134:135]
	global_load_dwordx4 v[146:149], v[122:123], off
	s_nop 0
	global_load_dwordx4 v[122:125], v[122:123], off offset:256
	v_ashrrev_i32_e32 v137, 31, v136
	v_readlane_b32 s8, v254, 14
	v_lshlrev_b64 v[152:153], 11, v[136:137]
	v_readlane_b32 s9, v254, 15
	s_waitcnt vmcnt(3)
	v_lshlrev_b32_e32 v154, 16, v138
	v_and_b32_e32 v155, 0xffff0000, v138
	v_lshlrev_b32_e32 v138, 16, v139
	v_and_b32_e32 v139, 0xffff0000, v139
	v_lshlrev_b32_e32 v156, 16, v140
	v_and_b32_e32 v157, 0xffff0000, v140
	v_lshlrev_b32_e32 v140, 16, v141
	v_and_b32_e32 v141, 0xffff0000, v141
	v_lshl_add_u64 v[152:153], s[8:9], 0, v[152:153]
	v_pk_fma_f32 v[128:129], v[138:139], s[78:79], v[128:129] op_sel_hi:[1,0,1]
	v_pk_fma_f32 v[126:127], v[154:155], s[78:79], v[126:127] op_sel_hi:[1,0,1]
	v_pk_fma_f32 v[132:133], v[140:141], s[78:79], v[132:133] op_sel_hi:[1,0,1]
	v_pk_fma_f32 v[130:131], v[156:157], s[78:79], v[130:131] op_sel_hi:[1,0,1]
	v_cvt_pk_f16_f32 v126, v126, v127
	v_cvt_pk_f16_f32 v127, v128, v129
	v_cvt_pk_f16_f32 v128, v130, v131
	v_cvt_pk_f16_f32 v129, v132, v133
	v_lshl_add_u64 v[130:131], v[152:153], 0, v[134:135]
	global_store_dwordx4 v[130:131], v[126:129], off sc0 sc1
	s_waitcnt vmcnt(3)
	v_lshlrev_b32_e32 v132, 16, v144
	v_and_b32_e32 v133, 0xffff0000, v144
	v_lshlrev_b32_e32 v126, 16, v142
	v_and_b32_e32 v127, 0xffff0000, v142
	v_lshlrev_b32_e32 v128, 16, v143
	v_and_b32_e32 v129, 0xffff0000, v143
	v_lshlrev_b32_e32 v138, 16, v145
	v_and_b32_e32 v139, 0xffff0000, v145
	v_pk_fma_f32 v[120:121], v[128:129], s[78:79], v[120:121] op_sel_hi:[1,0,1]
	v_pk_fma_f32 v[118:119], v[126:127], s[78:79], v[118:119] op_sel_hi:[1,0,1]
	v_pk_fma_f32 v[126:127], v[138:139], s[78:79], v[116:117] op_sel_hi:[1,0,1]
	v_pk_fma_f32 v[116:117], v[132:133], s[78:79], v[114:115] op_sel_hi:[1,0,1]
	v_cvt_pk_f16_f32 v114, v118, v119
	v_cvt_pk_f16_f32 v115, v120, v121
	v_cvt_pk_f16_f32 v116, v116, v117
	v_cvt_pk_f16_f32 v117, v126, v127
	global_store_dwordx4 v[130:131], v[114:117], off offset:256 sc0 sc1
	s_nop 1
	v_or_b32_e32 v114, 32, v136
	v_ashrrev_i32_e32 v115, 31, v114
	v_lshlrev_b64 v[126:127], 11, v[114:115]
	v_lshl_add_u64 v[114:115], s[28:29], 0, v[126:127]
	v_lshl_add_u64 v[118:119], v[114:115], 0, v[134:135]
	global_load_dwordx4 v[114:117], v[118:119], off
	s_nop 0
	global_load_dwordx4 v[118:121], v[118:119], off offset:256
	s_waitcnt vmcnt(5)
	v_lshlrev_b32_e32 v130, 16, v146
	v_and_b32_e32 v131, 0xffff0000, v146
	v_lshlrev_b32_e32 v132, 16, v147
	v_and_b32_e32 v133, 0xffff0000, v147
	v_lshlrev_b32_e32 v138, 16, v148
	v_and_b32_e32 v139, 0xffff0000, v148
	v_lshlrev_b32_e32 v140, 16, v149
	v_and_b32_e32 v141, 0xffff0000, v149
	v_lshl_add_u64 v[128:129], s[8:9], 0, v[150:151]
	v_pk_fma_f32 v[112:113], v[132:133], s[78:79], v[112:113] op_sel_hi:[1,0,1]
	v_pk_fma_f32 v[110:111], v[130:131], s[78:79], v[110:111] op_sel_hi:[1,0,1]
	v_pk_fma_f32 v[130:131], v[140:141], s[78:79], v[108:109] op_sel_hi:[1,0,1]
	v_pk_fma_f32 v[108:109], v[138:139], s[78:79], v[106:107] op_sel_hi:[1,0,1]
	v_cvt_pk_f16_f32 v106, v110, v111
	v_cvt_pk_f16_f32 v107, v112, v113
	v_cvt_pk_f16_f32 v108, v108, v109
	v_cvt_pk_f16_f32 v109, v130, v131
	v_lshl_add_u64 v[110:111], v[128:129], 0, v[134:135]
	global_store_dwordx4 v[110:111], v[106:109], off sc0 sc1
	s_waitcnt vmcnt(5)
	v_lshlrev_b32_e32 v112, 16, v124
	v_and_b32_e32 v113, 0xffff0000, v124
	v_lshlrev_b32_e32 v106, 16, v122
	v_and_b32_e32 v107, 0xffff0000, v122
	v_lshlrev_b32_e32 v108, 16, v123
	v_and_b32_e32 v109, 0xffff0000, v123
	v_lshlrev_b32_e32 v122, 16, v125
	v_and_b32_e32 v123, 0xffff0000, v125
	v_pk_fma_f32 v[104:105], v[108:109], s[78:79], v[104:105] op_sel_hi:[1,0,1]
	v_pk_fma_f32 v[102:103], v[106:107], s[78:79], v[102:103] op_sel_hi:[1,0,1]
	v_pk_fma_f32 v[106:107], v[122:123], s[78:79], v[100:101] op_sel_hi:[1,0,1]
	v_pk_fma_f32 v[100:101], v[112:113], s[78:79], v[98:99] op_sel_hi:[1,0,1]
	v_cvt_pk_f16_f32 v98, v102, v103
	v_cvt_pk_f16_f32 v99, v104, v105
	v_cvt_pk_f16_f32 v100, v100, v101
	v_cvt_pk_f16_f32 v101, v106, v107
	global_store_dwordx4 v[110:111], v[98:101], off offset:256 sc0 sc1
	s_nop 1
	v_or_b32_e32 v98, 48, v136
	v_ashrrev_i32_e32 v99, 31, v98
	v_lshlrev_b64 v[106:107], 11, v[98:99]
	v_lshl_add_u64 v[98:99], s[28:29], 0, v[106:107]
	v_lshl_add_u64 v[102:103], v[98:99], 0, v[134:135]
	global_load_dwordx4 v[98:101], v[102:103], off
	s_nop 0
	global_load_dwordx4 v[102:105], v[102:103], off offset:256
	s_waitcnt vmcnt(5)
; DI unsigned pk_f16(float lo, float hi) { f32x2_t v = {lo, hi}; return __builtin_bit_cast(unsigned, __builtin_convertvector(v, f16x2_t)); }
; DI float bflo(unsigned u) { return __uint_as_float(u << 16); }
; DI float bfhi(unsigned u) { return __uint_as_float(u & 0xffff0000u); }
; #define EPI_M _Pragma("unroll") for (int m = 0; m < 8; ++m)
; #define EPI_N2 _Pragma("unroll") for (int n2 = 0; n2 < 2; ++n2)
; DI void p6_phase(const Params& p, const float* xin, u16* dst, char* lds) {
;     ...
;     {
;       const u16* xinb = (const u16*)(ws + OFF_XB);
;       u32x4 xq[2][2];
;       EPI_N2 xq[0][n2] = *(const u32x4*)(xinb + (size_t)EPI_ROW(row0, 0) * D + EPI_COL(col0, 2 * n2));
;       EPI_M {
;         if (m < 7) EPI_N2 xq[(m + 1) & 1][n2] = *(const u32x4*)(xinb + (size_t)EPI_ROW(row0, m + 1) * D + EPI_COL(col0, 2 * n2));
;         EPI_N2 {
;           const u32x4 r = xq[m & 1][n2];
;           const f32x4 xa = {bflo(r[0]), bfhi(r[0]), bflo(r[1]), bfhi(r[1])}, xc = {bflo(r[2]), bfhi(r[2]), bflo(r[3]), bfhi(r[3])};
;           const f32x4 ya = xa * DN_ALPHA + ACC(m, 2 * n2), yc = xc * DN_ALPHA + ACC(m, 2 * n2 + 1);
;           u32x4 yo; yo[0] = pk_f16(ya[0], ya[1]); yo[1] = pk_f16(ya[2], ya[3]); yo[2] = pk_f16(yc[0], yc[1]); yo[3] = pk_f16(yc[2], yc[3]);
;           *(u32x4*)(dst + (size_t)EPI_ROW(row0, m) * D + EPI_COL(col0, 2 * n2)) = yo;
;         }
;         __builtin_amdgcn_sched_barrier(0);
;       }
;     }
	v_lshlrev_b32_e32 v110, 16, v114
	v_and_b32_e32 v111, 0xffff0000, v114
	v_lshlrev_b32_e32 v112, 16, v115
	v_and_b32_e32 v113, 0xffff0000, v115
	v_lshlrev_b32_e32 v114, 16, v116
	v_and_b32_e32 v115, 0xffff0000, v116
	v_lshlrev_b32_e32 v116, 16, v117
	v_and_b32_e32 v117, 0xffff0000, v117
	v_lshl_add_u64 v[108:109], s[8:9], 0, v[126:127]
	v_pk_fma_f32 v[96:97], v[112:113], s[78:79], v[96:97] op_sel_hi:[1,0,1]
	v_pk_fma_f32 v[94:95], v[110:111], s[78:79], v[94:95] op_sel_hi:[1,0,1]
	v_pk_fma_f32 v[110:111], v[116:117], s[78:79], v[92:93] op_sel_hi:[1,0,1]
	v_pk_fma_f32 v[92:93], v[114:115], s[78:79], v[90:91] op_sel_hi:[1,0,1]
	v_cvt_pk_f16_f32 v90, v94, v95
	v_cvt_pk_f16_f32 v91, v96, v97
	v_cvt_pk_f16_f32 v92, v92, v93
	v_cvt_pk_f16_f32 v93, v110, v111
	v_lshl_add_u64 v[94:95], v[108:109], 0, v[134:135]
	global_store_dwordx4 v[94:95], v[90:93], off sc0 sc1
	s_waitcnt vmcnt(5)
	v_lshlrev_b32_e32 v96, 16, v120
	v_and_b32_e32 v97, 0xffff0000, v120
	v_lshlrev_b32_e32 v90, 16, v118
	v_and_b32_e32 v91, 0xffff0000, v118
	v_lshlrev_b32_e32 v92, 16, v119
	v_and_b32_e32 v93, 0xffff0000, v119
	v_lshlrev_b32_e32 v108, 16, v121
	v_and_b32_e32 v109, 0xffff0000, v121
	v_pk_fma_f32 v[88:89], v[92:93], s[78:79], v[88:89] op_sel_hi:[1,0,1]
	v_pk_fma_f32 v[86:87], v[90:91], s[78:79], v[86:87] op_sel_hi:[1,0,1]
	v_pk_fma_f32 v[90:91], v[108:109], s[78:79], v[84:85] op_sel_hi:[1,0,1]
	v_pk_fma_f32 v[84:85], v[96:97], s[78:79], v[82:83] op_sel_hi:[1,0,1]
	v_cvt_pk_f16_f32 v82, v86, v87
	v_cvt_pk_f16_f32 v83, v88, v89
	v_cvt_pk_f16_f32 v84, v84, v85
	v_cvt_pk_f16_f32 v85, v90, v91
	global_store_dwordx4 v[94:95], v[82:85], off offset:256 sc0 sc1
	s_nop 1
	v_add_u32_e32 v82, 0x80, v136
	v_ashrrev_i32_e32 v83, 31, v82
	v_lshlrev_b64 v[90:91], 11, v[82:83]
	v_lshl_add_u64 v[82:83], s[28:29], 0, v[90:91]
	v_lshl_add_u64 v[86:87], v[82:83], 0, v[134:135]
	global_load_dwordx4 v[82:85], v[86:87], off
	s_nop 0
	global_load_dwordx4 v[86:89], v[86:87], off offset:256
	s_waitcnt vmcnt(5)
	v_lshlrev_b32_e32 v94, 16, v98
	v_and_b32_e32 v95, 0xffff0000, v98
	v_lshlrev_b32_e32 v96, 16, v99
	v_and_b32_e32 v97, 0xffff0000, v99
	v_lshlrev_b32_e32 v98, 16, v100
	v_and_b32_e32 v99, 0xffff0000, v100
	v_lshlrev_b32_e32 v100, 16, v101
	v_and_b32_e32 v101, 0xffff0000, v101
	v_lshl_add_u64 v[92:93], s[8:9], 0, v[106:107]
	v_pk_fma_f32 v[80:81], v[96:97], s[78:79], v[80:81] op_sel_hi:[1,0,1]
	v_pk_fma_f32 v[78:79], v[94:95], s[78:79], v[78:79] op_sel_hi:[1,0,1]
	v_pk_fma_f32 v[94:95], v[100:101], s[78:79], v[76:77] op_sel_hi:[1,0,1]
	v_pk_fma_f32 v[76:77], v[98:99], s[78:79], v[74:75] op_sel_hi:[1,0,1]
	v_cvt_pk_f16_f32 v74, v78, v79
	v_cvt_pk_f16_f32 v75, v80, v81
	v_cvt_pk_f16_f32 v76, v76, v77
	v_cvt_pk_f16_f32 v77, v94, v95
	v_lshl_add_u64 v[78:79], v[92:93], 0, v[134:135]
	global_store_dwordx4 v[78:79], v[74:77], off sc0 sc1
	s_waitcnt vmcnt(5)
	v_lshlrev_b32_e32 v80, 16, v104
	v_and_b32_e32 v81, 0xffff0000, v104
	v_lshlrev_b32_e32 v74, 16, v102
	v_and_b32_e32 v75, 0xffff0000, v102
	v_lshlrev_b32_e32 v76, 16, v103
	v_and_b32_e32 v77, 0xffff0000, v103
	v_lshlrev_b32_e32 v92, 16, v105
	v_and_b32_e32 v93, 0xffff0000, v105
	v_pk_fma_f32 v[72:73], v[76:77], s[78:79], v[72:73] op_sel_hi:[1,0,1]
	v_pk_fma_f32 v[70:71], v[74:75], s[78:79], v[70:71] op_sel_hi:[1,0,1]
	v_pk_fma_f32 v[74:75], v[92:93], s[78:79], v[68:69] op_sel_hi:[1,0,1]
	v_pk_fma_f32 v[68:69], v[80:81], s[78:79], v[66:67] op_sel_hi:[1,0,1]
	v_cvt_pk_f16_f32 v66, v70, v71
	v_cvt_pk_f16_f32 v67, v72, v73
	v_cvt_pk_f16_f32 v68, v68, v69
	v_cvt_pk_f16_f32 v69, v74, v75
	global_store_dwordx4 v[78:79], v[66:69], off offset:256 sc0 sc1
	s_nop 1
	v_add_u32_e32 v66, 0x90, v136
	v_ashrrev_i32_e32 v67, 31, v66
	v_lshlrev_b64 v[74:75], 11, v[66:67]
	v_lshl_add_u64 v[66:67], s[28:29], 0, v[74:75]
	v_lshl_add_u64 v[70:71], v[66:67], 0, v[134:135]
	global_load_dwordx4 v[66:69], v[70:71], off
	s_nop 0
	global_load_dwordx4 v[70:73], v[70:71], off offset:256
	s_waitcnt vmcnt(5)
	v_lshlrev_b32_e32 v78, 16, v82
	v_and_b32_e32 v79, 0xffff0000, v82
	v_lshlrev_b32_e32 v80, 16, v83
	v_and_b32_e32 v81, 0xffff0000, v83
	v_lshlrev_b32_e32 v82, 16, v84
	v_and_b32_e32 v83, 0xffff0000, v84
	v_lshlrev_b32_e32 v84, 16, v85
	v_and_b32_e32 v85, 0xffff0000, v85
	v_lshl_add_u64 v[76:77], s[8:9], 0, v[90:91]
	v_pk_fma_f32 v[62:63], v[80:81], s[78:79], v[62:63] op_sel_hi:[1,0,1]
	v_pk_fma_f32 v[60:61], v[78:79], s[78:79], v[60:61] op_sel_hi:[1,0,1]
	v_pk_fma_f32 v[78:79], v[84:85], s[78:79], v[58:59] op_sel_hi:[1,0,1]
	v_pk_fma_f32 v[58:59], v[82:83], s[78:79], v[56:57] op_sel_hi:[1,0,1]
	v_cvt_pk_f16_f32 v56, v60, v61
	v_cvt_pk_f16_f32 v57, v62, v63
	v_cvt_pk_f16_f32 v58, v58, v59
	v_cvt_pk_f16_f32 v59, v78, v79
	v_lshl_add_u64 v[60:61], v[76:77], 0, v[134:135]
	global_store_dwordx4 v[60:61], v[56:59], off sc0 sc1
	s_waitcnt vmcnt(5)
	v_lshlrev_b32_e32 v62, 16, v88
	v_and_b32_e32 v63, 0xffff0000, v88
	v_lshlrev_b32_e32 v56, 16, v86
	v_and_b32_e32 v57, 0xffff0000, v86
	v_lshlrev_b32_e32 v58, 16, v87
	v_and_b32_e32 v59, 0xffff0000, v87
	v_lshlrev_b32_e32 v76, 16, v89
	v_and_b32_e32 v77, 0xffff0000, v89
	v_pk_fma_f32 v[54:55], v[58:59], s[78:79], v[54:55] op_sel_hi:[1,0,1]
	v_pk_fma_f32 v[52:53], v[56:57], s[78:79], v[52:53] op_sel_hi:[1,0,1]
	v_pk_fma_f32 v[56:57], v[76:77], s[78:79], v[50:51] op_sel_hi:[1,0,1]
	v_pk_fma_f32 v[50:51], v[62:63], s[78:79], v[48:49] op_sel_hi:[1,0,1]
	v_cvt_pk_f16_f32 v48, v52, v53
	v_cvt_pk_f16_f32 v49, v54, v55
	v_cvt_pk_f16_f32 v50, v50, v51
	v_cvt_pk_f16_f32 v51, v56, v57
	global_store_dwordx4 v[60:61], v[48:51], off offset:256 sc0 sc1
	s_nop 1
	v_add_u32_e32 v48, 0xa0, v136
	v_ashrrev_i32_e32 v49, 31, v48
	v_lshlrev_b64 v[56:57], 11, v[48:49]
	v_lshl_add_u64 v[48:49], s[28:29], 0, v[56:57]
	v_lshl_add_u64 v[52:53], v[48:49], 0, v[134:135]
	global_load_dwordx4 v[48:51], v[52:53], off
	s_nop 0
	global_load_dwordx4 v[52:55], v[52:53], off offset:256
	s_waitcnt vmcnt(5)
; DI unsigned pk_f16(float lo, float hi) { f32x2_t v = {lo, hi}; return __builtin_bit_cast(unsigned, __builtin_convertvector(v, f16x2_t)); }
; DI float bflo(unsigned u) { return __uint_as_float(u << 16); }
; DI float bfhi(unsigned u) { return __uint_as_float(u & 0xffff0000u); }
; #define EPI_M _Pragma("unroll") for (int m = 0; m < 8; ++m)
; #define EPI_N2 _Pragma("unroll") for (int n2 = 0; n2 < 2; ++n2)
; DI void p6_phase(const Params& p, const float* xin, u16* dst, char* lds) {
;     ...
;     {
;       const u16* xinb = (const u16*)(ws + OFF_XB);
;       u32x4 xq[2][2];
;       EPI_N2 xq[0][n2] = *(const u32x4*)(xinb + (size_t)EPI_ROW(row0, 0) * D + EPI_COL(col0, 2 * n2));
;       EPI_M {
;         if (m < 7) EPI_N2 xq[(m + 1) & 1][n2] = *(const u32x4*)(xinb + (size_t)EPI_ROW(row0, m + 1) * D + EPI_COL(col0, 2 * n2));
;         EPI_N2 {
;           const u32x4 r = xq[m & 1][n2];
;           const f32x4 xa = {bflo(r[0]), bfhi(r[0]), bflo(r[1]), bfhi(r[1])}, xc = {bflo(r[2]), bfhi(r[2]), bflo(r[3]), bfhi(r[3])};
;           const f32x4 ya = xa * DN_ALPHA + ACC(m, 2 * n2), yc = xc * DN_ALPHA + ACC(m, 2 * n2 + 1);
;           u32x4 yo; yo[0] = pk_f16(ya[0], ya[1]); yo[1] = pk_f16(ya[2], ya[3]); yo[2] = pk_f16(yc[0], yc[1]); yo[3] = pk_f16(yc[2], yc[3]);
;           *(u32x4*)(dst + (size_t)EPI_ROW(row0, m) * D + EPI_COL(col0, 2 * n2)) = yo;
;         }
;         __builtin_amdgcn_sched_barrier(0);
;       }
;     }
	v_lshlrev_b32_e32 v60, 16, v66
	v_and_b32_e32 v61, 0xffff0000, v66
	v_lshlrev_b32_e32 v62, 16, v67
	v_and_b32_e32 v63, 0xffff0000, v67
	v_lshlrev_b32_e32 v66, 16, v68
	v_and_b32_e32 v67, 0xffff0000, v68
	v_lshlrev_b32_e32 v68, 16, v69
	v_and_b32_e32 v69, 0xffff0000, v69
	v_lshl_add_u64 v[58:59], s[8:9], 0, v[74:75]
	v_pk_fma_f32 v[46:47], v[62:63], s[78:79], v[46:47] op_sel_hi:[1,0,1]
	v_pk_fma_f32 v[44:45], v[60:61], s[78:79], v[44:45] op_sel_hi:[1,0,1]
	v_pk_fma_f32 v[60:61], v[68:69], s[78:79], v[42:43] op_sel_hi:[1,0,1]
	v_pk_fma_f32 v[42:43], v[66:67], s[78:79], v[40:41] op_sel_hi:[1,0,1]
	v_cvt_pk_f16_f32 v40, v44, v45
	v_cvt_pk_f16_f32 v41, v46, v47
	v_cvt_pk_f16_f32 v42, v42, v43
	v_cvt_pk_f16_f32 v43, v60, v61
	v_lshl_add_u64 v[44:45], v[58:59], 0, v[134:135]
	global_store_dwordx4 v[44:45], v[40:43], off sc0 sc1
	s_waitcnt vmcnt(5)
	v_lshlrev_b32_e32 v46, 16, v72
	v_and_b32_e32 v47, 0xffff0000, v72
	v_lshlrev_b32_e32 v40, 16, v70
	v_and_b32_e32 v41, 0xffff0000, v70
	v_lshlrev_b32_e32 v42, 16, v71
	v_and_b32_e32 v43, 0xffff0000, v71
	v_lshlrev_b32_e32 v58, 16, v73
	v_and_b32_e32 v59, 0xffff0000, v73
	v_pk_fma_f32 v[38:39], v[42:43], s[78:79], v[38:39] op_sel_hi:[1,0,1]
	v_pk_fma_f32 v[36:37], v[40:41], s[78:79], v[36:37] op_sel_hi:[1,0,1]
	v_pk_fma_f32 v[40:41], v[58:59], s[78:79], v[34:35] op_sel_hi:[1,0,1]
	v_pk_fma_f32 v[34:35], v[46:47], s[78:79], v[32:33] op_sel_hi:[1,0,1]
	v_cvt_pk_f16_f32 v32, v36, v37
	v_cvt_pk_f16_f32 v33, v38, v39
	v_cvt_pk_f16_f32 v34, v34, v35
	v_cvt_pk_f16_f32 v35, v40, v41
	global_store_dwordx4 v[44:45], v[32:35], off offset:256 sc0 sc1
	s_nop 1
	v_add_u32_e32 v32, 0xb0, v136
	v_ashrrev_i32_e32 v33, 31, v32
	v_lshlrev_b64 v[40:41], 11, v[32:33]
	v_lshl_add_u64 v[32:33], s[28:29], 0, v[40:41]
	v_lshl_add_u64 v[36:37], v[32:33], 0, v[134:135]
	global_load_dwordx4 v[32:35], v[36:37], off
	s_nop 0
	global_load_dwordx4 v[36:39], v[36:37], off offset:256
	s_waitcnt vmcnt(5)
	v_lshlrev_b32_e32 v44, 16, v48
	v_and_b32_e32 v45, 0xffff0000, v48
	v_lshlrev_b32_e32 v46, 16, v49
	v_and_b32_e32 v47, 0xffff0000, v49
	v_lshlrev_b32_e32 v48, 16, v50
	v_and_b32_e32 v49, 0xffff0000, v50
	v_lshlrev_b32_e32 v50, 16, v51
	v_and_b32_e32 v51, 0xffff0000, v51
	v_lshl_add_u64 v[42:43], s[8:9], 0, v[56:57]
	v_pk_fma_f32 v[30:31], v[46:47], s[78:79], v[30:31] op_sel_hi:[1,0,1]
	v_pk_fma_f32 v[28:29], v[44:45], s[78:79], v[28:29] op_sel_hi:[1,0,1]
	v_pk_fma_f32 v[44:45], v[50:51], s[78:79], v[26:27] op_sel_hi:[1,0,1]
	v_pk_fma_f32 v[26:27], v[48:49], s[78:79], v[24:25] op_sel_hi:[1,0,1]
	v_cvt_pk_f16_f32 v24, v28, v29
	v_cvt_pk_f16_f32 v25, v30, v31
	v_cvt_pk_f16_f32 v26, v26, v27
	v_cvt_pk_f16_f32 v27, v44, v45
	v_lshl_add_u64 v[28:29], v[42:43], 0, v[134:135]
	global_store_dwordx4 v[28:29], v[24:27], off sc0 sc1
	s_waitcnt vmcnt(5)
	v_lshlrev_b32_e32 v30, 16, v54
	v_and_b32_e32 v31, 0xffff0000, v54
	v_lshlrev_b32_e32 v24, 16, v52
	v_and_b32_e32 v25, 0xffff0000, v52
	v_lshlrev_b32_e32 v26, 16, v53
	v_and_b32_e32 v27, 0xffff0000, v53
	v_lshlrev_b32_e32 v42, 16, v55
	v_and_b32_e32 v43, 0xffff0000, v55
	v_pk_fma_f32 v[22:23], v[26:27], s[78:79], v[22:23] op_sel_hi:[1,0,1]
	v_pk_fma_f32 v[20:21], v[24:25], s[78:79], v[20:21] op_sel_hi:[1,0,1]
	v_pk_fma_f32 v[24:25], v[42:43], s[78:79], v[18:19] op_sel_hi:[1,0,1]
	v_pk_fma_f32 v[18:19], v[30:31], s[78:79], v[16:17] op_sel_hi:[1,0,1]
	v_cvt_pk_f16_f32 v16, v20, v21
	v_cvt_pk_f16_f32 v17, v22, v23
	v_cvt_pk_f16_f32 v18, v18, v19
	v_cvt_pk_f16_f32 v19, v24, v25
	global_store_dwordx4 v[28:29], v[16:19], off offset:256 sc0 sc1
	s_waitcnt vmcnt(3)
	s_nop 0
	v_lshlrev_b32_e32 v18, 16, v32
	v_and_b32_e32 v19, 0xffff0000, v32
	v_lshlrev_b32_e32 v20, 16, v33
	v_and_b32_e32 v21, 0xffff0000, v33
	v_lshlrev_b32_e32 v22, 16, v34
	v_and_b32_e32 v23, 0xffff0000, v34
	v_lshlrev_b32_e32 v24, 16, v35
	v_and_b32_e32 v25, 0xffff0000, v35
	v_lshl_add_u64 v[16:17], s[8:9], 0, v[40:41]
	v_pk_fma_f32 v[14:15], v[20:21], s[78:79], v[14:15] op_sel_hi:[1,0,1]
	v_pk_fma_f32 v[12:13], v[18:19], s[78:79], v[12:13] op_sel_hi:[1,0,1]
	v_pk_fma_f32 v[18:19], v[24:25], s[78:79], v[10:11] op_sel_hi:[1,0,1]
	v_pk_fma_f32 v[10:11], v[22:23], s[78:79], v[8:9] op_sel_hi:[1,0,1]
	v_cvt_pk_f16_f32 v8, v12, v13
	v_cvt_pk_f16_f32 v9, v14, v15
	v_cvt_pk_f16_f32 v10, v10, v11
	v_cvt_pk_f16_f32 v11, v18, v19
	v_lshl_add_u64 v[12:13], v[16:17], 0, v[134:135]
	global_store_dwordx4 v[12:13], v[8:11], off sc0 sc1
	s_waitcnt vmcnt(3)
	v_lshlrev_b32_e32 v14, 16, v38
	v_and_b32_e32 v15, 0xffff0000, v38
	v_lshlrev_b32_e32 v8, 16, v36
	v_and_b32_e32 v9, 0xffff0000, v36
	v_lshlrev_b32_e32 v10, 16, v37
	v_and_b32_e32 v11, 0xffff0000, v37
	v_lshlrev_b32_e32 v16, 16, v39
	v_and_b32_e32 v17, 0xffff0000, v39
	v_pk_fma_f32 v[6:7], v[10:11], s[78:79], v[6:7] op_sel_hi:[1,0,1]
	v_pk_fma_f32 v[4:5], v[8:9], s[78:79], v[4:5] op_sel_hi:[1,0,1]
	v_pk_fma_f32 v[8:9], v[16:17], s[78:79], v[2:3] op_sel_hi:[1,0,1]
	v_pk_fma_f32 v[2:3], v[14:15], s[78:79], v[0:1] op_sel_hi:[1,0,1]
	v_cvt_pk_f16_f32 v0, v4, v5
	v_cvt_pk_f16_f32 v1, v6, v7
	v_cvt_pk_f16_f32 v2, v2, v3
	v_cvt_pk_f16_f32 v3, v8, v9
	global_store_dwordx4 v[12:13], v[0:3], off offset:256 sc0 sc1
	v_readlane_b32 s8, v255, 7
	s_add_i32 s2, s2, s8
	s_cmpk_lt_i32 s2, 0x100
	v_readlane_b32 s9, v255, 8
	s_cbranch_scc0 .LBB0_1056

; DI unsigned pk_f16(float lo, float hi) { f32x2_t v = {lo, hi}; return __builtin_bit_cast(unsigned, __builtin_convertvector(v, f16x2_t)); }
; DI float bflo(unsigned u) { return __uint_as_float(u << 16); }
; DI float bfhi(unsigned u) { return __uint_as_float(u & 0xffff0000u); }
; #define EPI_M _Pragma("unroll") for (int m = 0; m < 8; ++m)
; #define EPI_N2 _Pragma("unroll") for (int n2 = 0; n2 < 2; ++n2)
; DI void p10_phase(const Params& p, int layer, u16* dst, char* lds) {
;     ...
;     {
;       u32x4 xq[2][2];
;       EPI_N2 xq[0][n2] = *(const u32x4*)(x1b + (size_t)EPI_ROW(row0, 0) * D + EPI_COL(col0, 2 * n2));
;       EPI_M {
;         if (m < 7) EPI_N2 xq[(m + 1) & 1][n2] = *(const u32x4*)(x1b + (size_t)EPI_ROW(row0, m + 1) * D + EPI_COL(col0, 2 * n2));
;         EPI_N2 {
;           const u32x4 r = xq[m & 1][n2];
;           const f32x4 xa = {bflo(r[0]), bfhi(r[0]), bflo(r[1]), bfhi(r[1])}, xc = {bflo(r[2]), bfhi(r[2]), bflo(r[3]), bfhi(r[3])};
;           const f32x4 ya = xa * DN_ALPHA + ACC(m, 2 * n2), yc = xc * DN_ALPHA + ACC(m, 2 * n2 + 1);
;           u32x4 yo; yo[0] = pk_f16(ya[0], ya[1]); yo[1] = pk_f16(ya[2], ya[3]); yo[2] = pk_f16(yc[0], yc[1]); yo[3] = pk_f16(yc[2], yc[3]);
;           *(u32x4*)(dst + (size_t)EPI_ROW(row0, m) * D + EPI_COL(col0, 2 * n2)) = yo;
;         }
;         __builtin_amdgcn_sched_barrier(0);
;       }
;     }
.LBB0_1240:
	s_or_b64 exec, exec, s[8:9]
	s_waitcnt vmcnt(0)
	s_barrier
	s_getreg_b32 s2, hwreg(HW_REG_HW_ID, 0, 6)
	s_lshl_b32 s2, s2, 2
	s_and_b32 s2, s2, 0xfc
	s_add_i32 s2, s2, 0x20040
	v_mov_b32_e32 v64, s2
	ds_read_b32 v64, v64
	v_readlane_b32 s8, v254, 20
	v_readlane_b32 s9, v254, 21
	s_waitcnt lgkmcnt(0)
	v_readfirstlane_b32 s2, v64
	s_nop 1
	v_lshl_or_b32 v64, s2, 6, v214
	v_readlane_b32 s2, v254, 12
	v_ashrrev_i32_e32 v122, 2, v64
	v_and_b32_e32 v137, 0xffffffc0, v122
	v_and_b32_e32 v136, 15, v64
	v_add_u32_e32 v122, s36, v137
	v_lshrrev_b32_e32 v64, 1, v64
	v_or_b32_e32 v122, v122, v136
	v_and_b32_e32 v64, 0x78, v64
	v_ashrrev_i32_e32 v123, 31, v122
	v_or_b32_e32 v124, s42, v64
	v_lshlrev_b64 v[122:123], 11, v[122:123]
	v_readlane_b32 s3, v254, 13
	v_ashrrev_i32_e32 v125, 31, v124
	v_lshlrev_b64 v[134:135], 1, v[124:125]
	v_lshl_add_u64 v[122:123], s[2:3], 0, v[122:123]
	v_or_b32_e32 v64, s36, v136
	v_lshl_add_u64 v[122:123], v[122:123], 0, v[134:135]
	v_add_u32_e32 v136, v64, v137
	global_load_dwordx4 v[138:141], v[122:123], off
	global_load_dwordx4 v[142:145], v[122:123], off offset:256
	v_or_b32_e32 v122, 16, v136
	v_ashrrev_i32_e32 v123, 31, v122
	v_lshlrev_b64 v[150:151], 11, v[122:123]
	v_lshl_add_u64 v[122:123], s[2:3], 0, v[150:151]
	v_lshl_add_u64 v[122:123], v[122:123], 0, v[134:135]
	global_load_dwordx4 v[146:149], v[122:123], off
	s_nop 0
	global_load_dwordx4 v[122:125], v[122:123], off offset:256
	v_ashrrev_i32_e32 v137, 31, v136
	v_lshlrev_b64 v[152:153], 11, v[136:137]
	v_lshl_add_u64 v[152:153], s[8:9], 0, v[152:153]
	s_waitcnt vmcnt(3)
	v_lshlrev_b32_e32 v154, 16, v138
	v_and_b32_e32 v155, 0xffff0000, v138
	v_lshlrev_b32_e32 v138, 16, v139
	v_and_b32_e32 v139, 0xffff0000, v139
	v_lshlrev_b32_e32 v156, 16, v140
	v_and_b32_e32 v157, 0xffff0000, v140
	v_lshlrev_b32_e32 v140, 16, v141
	v_and_b32_e32 v141, 0xffff0000, v141
	v_pk_fma_f32 v[128:129], v[138:139], s[78:79], v[128:129] op_sel_hi:[1,0,1]
	v_pk_fma_f32 v[126:127], v[154:155], s[78:79], v[126:127] op_sel_hi:[1,0,1]
	v_pk_fma_f32 v[132:133], v[140:141], s[78:79], v[132:133] op_sel_hi:[1,0,1]
	v_pk_fma_f32 v[130:131], v[156:157], s[78:79], v[130:131] op_sel_hi:[1,0,1]
	v_cvt_pk_f16_f32 v126, v126, v127
	v_cvt_pk_f16_f32 v127, v128, v129
	v_cvt_pk_f16_f32 v128, v130, v131
	v_cvt_pk_f16_f32 v129, v132, v133
	v_lshl_add_u64 v[130:131], v[152:153], 0, v[134:135]
	global_store_dwordx4 v[130:131], v[126:129], off sc0 sc1
	s_waitcnt vmcnt(3)
	v_lshlrev_b32_e32 v132, 16, v144
	v_and_b32_e32 v133, 0xffff0000, v144
	v_lshlrev_b32_e32 v126, 16, v142
	v_and_b32_e32 v127, 0xffff0000, v142
	v_lshlrev_b32_e32 v128, 16, v143
	v_and_b32_e32 v129, 0xffff0000, v143
	v_lshlrev_b32_e32 v138, 16, v145
	v_and_b32_e32 v139, 0xffff0000, v145
	v_pk_fma_f32 v[120:121], v[128:129], s[78:79], v[120:121] op_sel_hi:[1,0,1]
	v_pk_fma_f32 v[118:119], v[126:127], s[78:79], v[118:119] op_sel_hi:[1,0,1]
	v_pk_fma_f32 v[126:127], v[138:139], s[78:79], v[116:117] op_sel_hi:[1,0,1]
	v_pk_fma_f32 v[116:117], v[132:133], s[78:79], v[114:115] op_sel_hi:[1,0,1]
	v_cvt_pk_f16_f32 v114, v118, v119
	v_cvt_pk_f16_f32 v115, v120, v121
	v_cvt_pk_f16_f32 v116, v116, v117
	v_cvt_pk_f16_f32 v117, v126, v127
	global_store_dwordx4 v[130:131], v[114:117], off offset:256 sc0 sc1
	s_nop 1
	v_or_b32_e32 v114, 32, v136
	v_ashrrev_i32_e32 v115, 31, v114
	v_lshlrev_b64 v[126:127], 11, v[114:115]
	v_lshl_add_u64 v[114:115], s[2:3], 0, v[126:127]
	v_lshl_add_u64 v[118:119], v[114:115], 0, v[134:135]
	global_load_dwordx4 v[114:117], v[118:119], off
	s_nop 0
	global_load_dwordx4 v[118:121], v[118:119], off offset:256
	s_waitcnt vmcnt(5)
	v_lshlrev_b32_e32 v130, 16, v146
	v_and_b32_e32 v131, 0xffff0000, v146
	v_lshlrev_b32_e32 v132, 16, v147
	v_and_b32_e32 v133, 0xffff0000, v147
	v_lshlrev_b32_e32 v138, 16, v148
	v_and_b32_e32 v139, 0xffff0000, v148
	v_lshlrev_b32_e32 v140, 16, v149
	v_and_b32_e32 v141, 0xffff0000, v149
	v_lshl_add_u64 v[128:129], s[8:9], 0, v[150:151]
	v_pk_fma_f32 v[112:113], v[132:133], s[78:79], v[112:113] op_sel_hi:[1,0,1]
	v_pk_fma_f32 v[110:111], v[130:131], s[78:79], v[110:111] op_sel_hi:[1,0,1]
	v_pk_fma_f32 v[130:131], v[140:141], s[78:79], v[108:109] op_sel_hi:[1,0,1]
	v_pk_fma_f32 v[108:109], v[138:139], s[78:79], v[106:107] op_sel_hi:[1,0,1]
	v_cvt_pk_f16_f32 v106, v110, v111
	v_cvt_pk_f16_f32 v107, v112, v113
	v_cvt_pk_f16_f32 v108, v108, v109
	v_cvt_pk_f16_f32 v109, v130, v131
	v_lshl_add_u64 v[110:111], v[128:129], 0, v[134:135]
	global_store_dwordx4 v[110:111], v[106:109], off sc0 sc1
	s_waitcnt vmcnt(5)
	v_lshlrev_b32_e32 v112, 16, v124
	v_and_b32_e32 v113, 0xffff0000, v124
	v_lshlrev_b32_e32 v106, 16, v122
	v_and_b32_e32 v107, 0xffff0000, v122
	v_lshlrev_b32_e32 v108, 16, v123
	v_and_b32_e32 v109, 0xffff0000, v123
	v_lshlrev_b32_e32 v122, 16, v125
	v_and_b32_e32 v123, 0xffff0000, v125
	v_pk_fma_f32 v[104:105], v[108:109], s[78:79], v[104:105] op_sel_hi:[1,0,1]
	v_pk_fma_f32 v[102:103], v[106:107], s[78:79], v[102:103] op_sel_hi:[1,0,1]
	v_pk_fma_f32 v[106:107], v[122:123], s[78:79], v[100:101] op_sel_hi:[1,0,1]
	v_pk_fma_f32 v[100:101], v[112:113], s[78:79], v[98:99] op_sel_hi:[1,0,1]
	v_cvt_pk_f16_f32 v98, v102, v103
	v_cvt_pk_f16_f32 v99, v104, v105
	v_cvt_pk_f16_f32 v100, v100, v101
	v_cvt_pk_f16_f32 v101, v106, v107
	global_store_dwordx4 v[110:111], v[98:101], off offset:256 sc0 sc1
	s_nop 1
	v_or_b32_e32 v98, 48, v136
	v_ashrrev_i32_e32 v99, 31, v98
	v_lshlrev_b64 v[106:107], 11, v[98:99]
	v_lshl_add_u64 v[98:99], s[2:3], 0, v[106:107]
	v_lshl_add_u64 v[102:103], v[98:99], 0, v[134:135]
	global_load_dwordx4 v[98:101], v[102:103], off
	s_nop 0
	global_load_dwordx4 v[102:105], v[102:103], off offset:256
	s_waitcnt vmcnt(5)
; DI unsigned pk_f16(float lo, float hi) { f32x2_t v = {lo, hi}; return __builtin_bit_cast(unsigned, __builtin_convertvector(v, f16x2_t)); }
; DI float bflo(unsigned u) { return __uint_as_float(u << 16); }
; DI float bfhi(unsigned u) { return __uint_as_float(u & 0xffff0000u); }
; #define EPI_M _Pragma("unroll") for (int m = 0; m < 8; ++m)
; #define EPI_N2 _Pragma("unroll") for (int n2 = 0; n2 < 2; ++n2)
; DI void p10_phase(const Params& p, int layer, u16* dst, char* lds) {
;     ...
;     {
;       u32x4 xq[2][2];
;       EPI_N2 xq[0][n2] = *(const u32x4*)(x1b + (size_t)EPI_ROW(row0, 0) * D + EPI_COL(col0, 2 * n2));
;       EPI_M {
;         if (m < 7) EPI_N2 xq[(m + 1) & 1][n2] = *(const u32x4*)(x1b + (size_t)EPI_ROW(row0, m + 1) * D + EPI_COL(col0, 2 * n2));
;         EPI_N2 {
;           const u32x4 r = xq[m & 1][n2];
;           const f32x4 xa = {bflo(r[0]), bfhi(r[0]), bflo(r[1]), bfhi(r[1])}, xc = {bflo(r[2]), bfhi(r[2]), bflo(r[3]), bfhi(r[3])};
;           const f32x4 ya = xa * DN_ALPHA + ACC(m, 2 * n2), yc = xc * DN_ALPHA + ACC(m, 2 * n2 + 1);
;           u32x4 yo; yo[0] = pk_f16(ya[0], ya[1]); yo[1] = pk_f16(ya[2], ya[3]); yo[2] = pk_f16(yc[0], yc[1]); yo[3] = pk_f16(yc[2], yc[3]);
;           *(u32x4*)(dst + (size_t)EPI_ROW(row0, m) * D + EPI_COL(col0, 2 * n2)) = yo;
;         }
;         __builtin_amdgcn_sched_barrier(0);
;       }
;     }
	v_lshlrev_b32_e32 v110, 16, v114
	v_and_b32_e32 v111, 0xffff0000, v114
	v_lshlrev_b32_e32 v112, 16, v115
	v_and_b32_e32 v113, 0xffff0000, v115
	v_lshlrev_b32_e32 v114, 16, v116
	v_and_b32_e32 v115, 0xffff0000, v116
	v_lshlrev_b32_e32 v116, 16, v117
	v_and_b32_e32 v117, 0xffff0000, v117
	v_lshl_add_u64 v[108:109], s[8:9], 0, v[126:127]
	v_pk_fma_f32 v[96:97], v[112:113], s[78:79], v[96:97] op_sel_hi:[1,0,1]
	v_pk_fma_f32 v[94:95], v[110:111], s[78:79], v[94:95] op_sel_hi:[1,0,1]
	v_pk_fma_f32 v[110:111], v[116:117], s[78:79], v[92:93] op_sel_hi:[1,0,1]
	v_pk_fma_f32 v[92:93], v[114:115], s[78:79], v[90:91] op_sel_hi:[1,0,1]
	v_cvt_pk_f16_f32 v90, v94, v95
	v_cvt_pk_f16_f32 v91, v96, v97
	v_cvt_pk_f16_f32 v92, v92, v93
	v_cvt_pk_f16_f32 v93, v110, v111
	v_lshl_add_u64 v[94:95], v[108:109], 0, v[134:135]
	global_store_dwordx4 v[94:95], v[90:93], off sc0 sc1
	s_waitcnt vmcnt(5)
	v_lshlrev_b32_e32 v96, 16, v120
	v_and_b32_e32 v97, 0xffff0000, v120
	v_lshlrev_b32_e32 v90, 16, v118
	v_and_b32_e32 v91, 0xffff0000, v118
	v_lshlrev_b32_e32 v92, 16, v119
	v_and_b32_e32 v93, 0xffff0000, v119
	v_lshlrev_b32_e32 v108, 16, v121
	v_and_b32_e32 v109, 0xffff0000, v121
	v_pk_fma_f32 v[88:89], v[92:93], s[78:79], v[88:89] op_sel_hi:[1,0,1]
	v_pk_fma_f32 v[86:87], v[90:91], s[78:79], v[86:87] op_sel_hi:[1,0,1]
	v_pk_fma_f32 v[90:91], v[108:109], s[78:79], v[84:85] op_sel_hi:[1,0,1]
	v_pk_fma_f32 v[84:85], v[96:97], s[78:79], v[82:83] op_sel_hi:[1,0,1]
	v_cvt_pk_f16_f32 v82, v86, v87
	v_cvt_pk_f16_f32 v83, v88, v89
	v_cvt_pk_f16_f32 v84, v84, v85
	v_cvt_pk_f16_f32 v85, v90, v91
	global_store_dwordx4 v[94:95], v[82:85], off offset:256 sc0 sc1
	s_nop 1
	v_add_u32_e32 v82, 0x80, v136
	v_ashrrev_i32_e32 v83, 31, v82
	v_lshlrev_b64 v[90:91], 11, v[82:83]
	v_lshl_add_u64 v[82:83], s[2:3], 0, v[90:91]
	v_lshl_add_u64 v[86:87], v[82:83], 0, v[134:135]
	global_load_dwordx4 v[82:85], v[86:87], off
	s_nop 0
	global_load_dwordx4 v[86:89], v[86:87], off offset:256
	s_waitcnt vmcnt(5)
	v_lshlrev_b32_e32 v94, 16, v98
	v_and_b32_e32 v95, 0xffff0000, v98
	v_lshlrev_b32_e32 v96, 16, v99
	v_and_b32_e32 v97, 0xffff0000, v99
	v_lshlrev_b32_e32 v98, 16, v100
	v_and_b32_e32 v99, 0xffff0000, v100
	v_lshlrev_b32_e32 v100, 16, v101
	v_and_b32_e32 v101, 0xffff0000, v101
	v_lshl_add_u64 v[92:93], s[8:9], 0, v[106:107]
	v_pk_fma_f32 v[80:81], v[96:97], s[78:79], v[80:81] op_sel_hi:[1,0,1]
	v_pk_fma_f32 v[78:79], v[94:95], s[78:79], v[78:79] op_sel_hi:[1,0,1]
	v_pk_fma_f32 v[94:95], v[100:101], s[78:79], v[76:77] op_sel_hi:[1,0,1]
	v_pk_fma_f32 v[76:77], v[98:99], s[78:79], v[74:75] op_sel_hi:[1,0,1]
	v_cvt_pk_f16_f32 v74, v78, v79
	v_cvt_pk_f16_f32 v75, v80, v81
	v_cvt_pk_f16_f32 v76, v76, v77
	v_cvt_pk_f16_f32 v77, v94, v95
	v_lshl_add_u64 v[78:79], v[92:93], 0, v[134:135]
	global_store_dwordx4 v[78:79], v[74:77], off sc0 sc1
	s_waitcnt vmcnt(5)
	v_lshlrev_b32_e32 v80, 16, v104
	v_and_b32_e32 v81, 0xffff0000, v104
	v_lshlrev_b32_e32 v74, 16, v102
	v_and_b32_e32 v75, 0xffff0000, v102
	v_lshlrev_b32_e32 v76, 16, v103
	v_and_b32_e32 v77, 0xffff0000, v103
	v_lshlrev_b32_e32 v92, 16, v105
	v_and_b32_e32 v93, 0xffff0000, v105
	v_pk_fma_f32 v[72:73], v[76:77], s[78:79], v[72:73] op_sel_hi:[1,0,1]
	v_pk_fma_f32 v[70:71], v[74:75], s[78:79], v[70:71] op_sel_hi:[1,0,1]
	v_pk_fma_f32 v[74:75], v[92:93], s[78:79], v[68:69] op_sel_hi:[1,0,1]
	v_pk_fma_f32 v[68:69], v[80:81], s[78:79], v[66:67] op_sel_hi:[1,0,1]
	v_cvt_pk_f16_f32 v66, v70, v71
	v_cvt_pk_f16_f32 v67, v72, v73
	v_cvt_pk_f16_f32 v68, v68, v69
	v_cvt_pk_f16_f32 v69, v74, v75
	global_store_dwordx4 v[78:79], v[66:69], off offset:256 sc0 sc1
	s_nop 1
	v_add_u32_e32 v66, 0x90, v136
	v_ashrrev_i32_e32 v67, 31, v66
	v_lshlrev_b64 v[74:75], 11, v[66:67]
	v_lshl_add_u64 v[66:67], s[2:3], 0, v[74:75]
	v_lshl_add_u64 v[70:71], v[66:67], 0, v[134:135]
	global_load_dwordx4 v[66:69], v[70:71], off
	s_nop 0
	global_load_dwordx4 v[70:73], v[70:71], off offset:256
	s_waitcnt vmcnt(5)
	v_lshlrev_b32_e32 v78, 16, v82
	v_and_b32_e32 v79, 0xffff0000, v82
	v_lshlrev_b32_e32 v80, 16, v83
	v_and_b32_e32 v81, 0xffff0000, v83
	v_lshlrev_b32_e32 v82, 16, v84
	v_and_b32_e32 v83, 0xffff0000, v84
	v_lshlrev_b32_e32 v84, 16, v85
	v_and_b32_e32 v85, 0xffff0000, v85
	v_lshl_add_u64 v[76:77], s[8:9], 0, v[90:91]
	v_pk_fma_f32 v[62:63], v[80:81], s[78:79], v[62:63] op_sel_hi:[1,0,1]
	v_pk_fma_f32 v[60:61], v[78:79], s[78:79], v[60:61] op_sel_hi:[1,0,1]
	v_pk_fma_f32 v[78:79], v[84:85], s[78:79], v[58:59] op_sel_hi:[1,0,1]
	v_pk_fma_f32 v[58:59], v[82:83], s[78:79], v[56:57] op_sel_hi:[1,0,1]
	v_cvt_pk_f16_f32 v56, v60, v61
	v_cvt_pk_f16_f32 v57, v62, v63
	v_cvt_pk_f16_f32 v58, v58, v59
	v_cvt_pk_f16_f32 v59, v78, v79
	v_lshl_add_u64 v[60:61], v[76:77], 0, v[134:135]
	global_store_dwordx4 v[60:61], v[56:59], off sc0 sc1
	s_waitcnt vmcnt(5)
	v_lshlrev_b32_e32 v62, 16, v88
	v_and_b32_e32 v63, 0xffff0000, v88
	v_lshlrev_b32_e32 v56, 16, v86
	v_and_b32_e32 v57, 0xffff0000, v86
	v_lshlrev_b32_e32 v58, 16, v87
	v_and_b32_e32 v59, 0xffff0000, v87
	v_lshlrev_b32_e32 v76, 16, v89
	v_and_b32_e32 v77, 0xffff0000, v89
	v_pk_fma_f32 v[54:55], v[58:59], s[78:79], v[54:55] op_sel_hi:[1,0,1]
	v_pk_fma_f32 v[52:53], v[56:57], s[78:79], v[52:53] op_sel_hi:[1,0,1]
	v_pk_fma_f32 v[56:57], v[76:77], s[78:79], v[50:51] op_sel_hi:[1,0,1]
	v_pk_fma_f32 v[50:51], v[62:63], s[78:79], v[48:49] op_sel_hi:[1,0,1]
	v_cvt_pk_f16_f32 v48, v52, v53
	v_cvt_pk_f16_f32 v49, v54, v55
	v_cvt_pk_f16_f32 v50, v50, v51
	v_cvt_pk_f16_f32 v51, v56, v57
	global_store_dwordx4 v[60:61], v[48:51], off offset:256 sc0 sc1
	s_nop 1
	v_add_u32_e32 v48, 0xa0, v136
	v_ashrrev_i32_e32 v49, 31, v48
	v_lshlrev_b64 v[56:57], 11, v[48:49]
	v_lshl_add_u64 v[48:49], s[2:3], 0, v[56:57]
	v_lshl_add_u64 v[52:53], v[48:49], 0, v[134:135]
	global_load_dwordx4 v[48:51], v[52:53], off
	s_nop 0
	global_load_dwordx4 v[52:55], v[52:53], off offset:256
	s_waitcnt vmcnt(5)
; DI unsigned pk_f16(float lo, float hi) { f32x2_t v = {lo, hi}; return __builtin_bit_cast(unsigned, __builtin_convertvector(v, f16x2_t)); }
; DI float bflo(unsigned u) { return __uint_as_float(u << 16); }
; DI float bfhi(unsigned u) { return __uint_as_float(u & 0xffff0000u); }
; #define EPI_M _Pragma("unroll") for (int m = 0; m < 8; ++m)
; #define EPI_N2 _Pragma("unroll") for (int n2 = 0; n2 < 2; ++n2)
; DI void p10_phase(const Params& p, int layer, u16* dst, char* lds) {
;     ...
;     {
;       u32x4 xq[2][2];
;       EPI_N2 xq[0][n2] = *(const u32x4*)(x1b + (size_t)EPI_ROW(row0, 0) * D + EPI_COL(col0, 2 * n2));
;       EPI_M {
;         if (m < 7) EPI_N2 xq[(m + 1) & 1][n2] = *(const u32x4*)(x1b + (size_t)EPI_ROW(row0, m + 1) * D + EPI_COL(col0, 2 * n2));
;         EPI_N2 {
;           const u32x4 r = xq[m & 1][n2];
;           const f32x4 xa = {bflo(r[0]), bfhi(r[0]), bflo(r[1]), bfhi(r[1])}, xc = {bflo(r[2]), bfhi(r[2]), bflo(r[3]), bfhi(r[3])};
;           const f32x4 ya = xa * DN_ALPHA + ACC(m, 2 * n2), yc = xc * DN_ALPHA + ACC(m, 2 * n2 + 1);
;           u32x4 yo; yo[0] = pk_f16(ya[0], ya[1]); yo[1] = pk_f16(ya[2], ya[3]); yo[2] = pk_f16(yc[0], yc[1]); yo[3] = pk_f16(yc[2], yc[3]);
;           *(u32x4*)(dst + (size_t)EPI_ROW(row0, m) * D + EPI_COL(col0, 2 * n2)) = yo;
;         }
;         __builtin_amdgcn_sched_barrier(0);
;       }
;     }
	v_lshlrev_b32_e32 v60, 16, v66
	v_and_b32_e32 v61, 0xffff0000, v66
	v_lshlrev_b32_e32 v62, 16, v67
	v_and_b32_e32 v63, 0xffff0000, v67
	v_lshlrev_b32_e32 v66, 16, v68
	v_and_b32_e32 v67, 0xffff0000, v68
	v_lshlrev_b32_e32 v68, 16, v69
	v_and_b32_e32 v69, 0xffff0000, v69
	v_lshl_add_u64 v[58:59], s[8:9], 0, v[74:75]
	v_pk_fma_f32 v[46:47], v[62:63], s[78:79], v[46:47] op_sel_hi:[1,0,1]
	v_pk_fma_f32 v[44:45], v[60:61], s[78:79], v[44:45] op_sel_hi:[1,0,1]
	v_pk_fma_f32 v[60:61], v[68:69], s[78:79], v[42:43] op_sel_hi:[1,0,1]
	v_pk_fma_f32 v[42:43], v[66:67], s[78:79], v[40:41] op_sel_hi:[1,0,1]
	v_cvt_pk_f16_f32 v40, v44, v45
	v_cvt_pk_f16_f32 v41, v46, v47
	v_cvt_pk_f16_f32 v42, v42, v43
	v_cvt_pk_f16_f32 v43, v60, v61
	v_lshl_add_u64 v[44:45], v[58:59], 0, v[134:135]
	global_store_dwordx4 v[44:45], v[40:43], off sc0 sc1
	s_waitcnt vmcnt(5)
	v_lshlrev_b32_e32 v46, 16, v72
	v_and_b32_e32 v47, 0xffff0000, v72
	v_lshlrev_b32_e32 v40, 16, v70
	v_and_b32_e32 v41, 0xffff0000, v70
	v_lshlrev_b32_e32 v42, 16, v71
	v_and_b32_e32 v43, 0xffff0000, v71
	v_lshlrev_b32_e32 v58, 16, v73
	v_and_b32_e32 v59, 0xffff0000, v73
	v_pk_fma_f32 v[38:39], v[42:43], s[78:79], v[38:39] op_sel_hi:[1,0,1]
	v_pk_fma_f32 v[36:37], v[40:41], s[78:79], v[36:37] op_sel_hi:[1,0,1]
	v_pk_fma_f32 v[40:41], v[58:59], s[78:79], v[34:35] op_sel_hi:[1,0,1]
	v_pk_fma_f32 v[34:35], v[46:47], s[78:79], v[32:33] op_sel_hi:[1,0,1]
	v_cvt_pk_f16_f32 v32, v36, v37
	v_cvt_pk_f16_f32 v33, v38, v39
	v_cvt_pk_f16_f32 v34, v34, v35
	v_cvt_pk_f16_f32 v35, v40, v41
	global_store_dwordx4 v[44:45], v[32:35], off offset:256 sc0 sc1
	s_nop 1
	v_add_u32_e32 v32, 0xb0, v136
	v_ashrrev_i32_e32 v33, 31, v32
	v_lshlrev_b64 v[40:41], 11, v[32:33]
	v_lshl_add_u64 v[32:33], s[2:3], 0, v[40:41]
	v_lshl_add_u64 v[36:37], v[32:33], 0, v[134:135]
	global_load_dwordx4 v[32:35], v[36:37], off
	s_nop 0
	global_load_dwordx4 v[36:39], v[36:37], off offset:256
	s_waitcnt vmcnt(5)
	v_lshlrev_b32_e32 v44, 16, v48
	v_and_b32_e32 v45, 0xffff0000, v48
	v_lshlrev_b32_e32 v46, 16, v49
	v_and_b32_e32 v47, 0xffff0000, v49
	v_lshlrev_b32_e32 v48, 16, v50
	v_and_b32_e32 v49, 0xffff0000, v50
	v_lshlrev_b32_e32 v50, 16, v51
	v_and_b32_e32 v51, 0xffff0000, v51
	v_lshl_add_u64 v[42:43], s[8:9], 0, v[56:57]
	v_pk_fma_f32 v[30:31], v[46:47], s[78:79], v[30:31] op_sel_hi:[1,0,1]
	v_pk_fma_f32 v[28:29], v[44:45], s[78:79], v[28:29] op_sel_hi:[1,0,1]
	v_pk_fma_f32 v[44:45], v[50:51], s[78:79], v[26:27] op_sel_hi:[1,0,1]
	v_pk_fma_f32 v[26:27], v[48:49], s[78:79], v[24:25] op_sel_hi:[1,0,1]
	v_cvt_pk_f16_f32 v24, v28, v29
	v_cvt_pk_f16_f32 v25, v30, v31
	v_cvt_pk_f16_f32 v26, v26, v27
	v_cvt_pk_f16_f32 v27, v44, v45
	v_lshl_add_u64 v[28:29], v[42:43], 0, v[134:135]
	global_store_dwordx4 v[28:29], v[24:27], off sc0 sc1
	s_waitcnt vmcnt(5)
	v_lshlrev_b32_e32 v30, 16, v54
	v_and_b32_e32 v31, 0xffff0000, v54
	v_lshlrev_b32_e32 v24, 16, v52
	v_and_b32_e32 v25, 0xffff0000, v52
	v_lshlrev_b32_e32 v26, 16, v53
	v_and_b32_e32 v27, 0xffff0000, v53
	v_lshlrev_b32_e32 v42, 16, v55
	v_and_b32_e32 v43, 0xffff0000, v55
	v_pk_fma_f32 v[22:23], v[26:27], s[78:79], v[22:23] op_sel_hi:[1,0,1]
	v_pk_fma_f32 v[20:21], v[24:25], s[78:79], v[20:21] op_sel_hi:[1,0,1]
	v_pk_fma_f32 v[24:25], v[42:43], s[78:79], v[18:19] op_sel_hi:[1,0,1]
	v_pk_fma_f32 v[18:19], v[30:31], s[78:79], v[16:17] op_sel_hi:[1,0,1]
	v_cvt_pk_f16_f32 v16, v20, v21
	v_cvt_pk_f16_f32 v17, v22, v23
	v_cvt_pk_f16_f32 v18, v18, v19
	v_cvt_pk_f16_f32 v19, v24, v25
	global_store_dwordx4 v[28:29], v[16:19], off offset:256 sc0 sc1
	s_waitcnt vmcnt(3)
	s_nop 0
	v_lshlrev_b32_e32 v18, 16, v32
	v_and_b32_e32 v19, 0xffff0000, v32
	v_lshlrev_b32_e32 v20, 16, v33
	v_and_b32_e32 v21, 0xffff0000, v33
	v_lshlrev_b32_e32 v22, 16, v34
	v_and_b32_e32 v23, 0xffff0000, v34
	v_lshlrev_b32_e32 v24, 16, v35
	v_and_b32_e32 v25, 0xffff0000, v35
	v_lshl_add_u64 v[16:17], s[8:9], 0, v[40:41]
	v_pk_fma_f32 v[14:15], v[20:21], s[78:79], v[14:15] op_sel_hi:[1,0,1]
	v_pk_fma_f32 v[12:13], v[18:19], s[78:79], v[12:13] op_sel_hi:[1,0,1]
	v_pk_fma_f32 v[18:19], v[24:25], s[78:79], v[10:11] op_sel_hi:[1,0,1]
	v_pk_fma_f32 v[10:11], v[22:23], s[78:79], v[8:9] op_sel_hi:[1,0,1]
	v_cvt_pk_f16_f32 v8, v12, v13
	v_cvt_pk_f16_f32 v9, v14, v15
	v_cvt_pk_f16_f32 v10, v10, v11
	v_cvt_pk_f16_f32 v11, v18, v19
	v_lshl_add_u64 v[12:13], v[16:17], 0, v[134:135]
	global_store_dwordx4 v[12:13], v[8:11], off sc0 sc1
	s_waitcnt vmcnt(3)
	v_lshlrev_b32_e32 v14, 16, v38
	v_and_b32_e32 v15, 0xffff0000, v38
	v_lshlrev_b32_e32 v8, 16, v36
	v_and_b32_e32 v9, 0xffff0000, v36
	v_lshlrev_b32_e32 v10, 16, v37
	v_and_b32_e32 v11, 0xffff0000, v37
	v_lshlrev_b32_e32 v16, 16, v39
	v_and_b32_e32 v17, 0xffff0000, v39
	v_pk_fma_f32 v[6:7], v[10:11], s[78:79], v[6:7] op_sel_hi:[1,0,1]
	v_pk_fma_f32 v[4:5], v[8:9], s[78:79], v[4:5] op_sel_hi:[1,0,1]
	v_pk_fma_f32 v[8:9], v[16:17], s[78:79], v[2:3] op_sel_hi:[1,0,1]
	v_pk_fma_f32 v[2:3], v[14:15], s[78:79], v[0:1] op_sel_hi:[1,0,1]
	v_cvt_pk_f16_f32 v0, v4, v5
	v_cvt_pk_f16_f32 v1, v6, v7
	v_cvt_pk_f16_f32 v2, v2, v3
	v_cvt_pk_f16_f32 v3, v8, v9
	global_store_dwordx4 v[12:13], v[0:3], off offset:256 sc0 sc1
	v_readlane_b32 s2, v255, 7
	s_add_i32 s50, s50, s2
	s_cmpk_lt_i32 s50, 0x100
	v_readlane_b32 s3, v255, 8
	s_cbranch_scc0 .LBB0_1269
